# LRU epilogue: u operand read back from the staged A tile in LDS (ds_read_u16) instead of 32 serialized global loads; stores no longer waited
# baseline (speedup 1.0000x reference)
; template <int EPI>
; __device__ __forceinline__ void gemm_tile(const Params& p, const EpiArgs& ea, const bf16_t* __restrict__ A, int lda,
;                                           const bf16_t* __restrict__ Bt, int K, int m0, int n0, char* smem) {
;     ...
;   const int srow = tid >> 3, sch = (tid & 7) * 8;
;   const bf16_t* ap = A + (size_t)(m0 + srow) * lda + sch;
;   const bf16_t* bp = Bt + (size_t)(n0 + srow) * K + sch;
;   const size_t a_step = (size_t)64 * lda, b_step = (size_t)64 * K;
;   uint4 ra[4], rb[2];
;   const int nk = K >> 6;
; #pragma unroll
;   for (int i = 0; i < 4; ++i) ra[i] = *(const uint4*)(ap + i * a_step);
; #pragma unroll
;   for (int i = 0; i < 2; ++i) rb[i] = *(const uint4*)(bp + i * b_step);
; #pragma unroll
;   for (int i = 0; i < 4; ++i) *(uint4*)(sA + (srow + i * 64) * LDT + sch) = ra[i];
; #pragma unroll
;   for (int i = 0; i < 2; ++i) *(uint4*)(sB + (srow + i * 64) * LDT + sch) = rb[i];
;   __syncthreads();
;   for (int kt = 0; kt < nk; ++kt) {
;     const int buf = kt & 1;
;     if (kt + 1 < nk) {
; #pragma unroll
;       for (int i = 0; i < 4; ++i) ra[i] = *(const uint4*)(ap + i * a_step + (kt + 1) * 64);
; #pragma unroll
;       for (int i = 0; i < 2; ++i) rb[i] = *(const uint4*)(bp + i * b_step + (kt + 1) * 64);
;     }
;     const bf16_t* cA = sA + buf * 256 * LDT + (wm * 64 + fr) * LDT + fq * 8;
;     const bf16_t* cB = sB + buf * 128 * LDT + (wn * 64 + fr) * LDT + fq * 8;
; #pragma unroll
;     for (int ks = 0; ks < 2; ++ks) {
;       bf16x8 af[4], bfg[4];
; #pragma unroll
;       for (int mi = 0; mi < 4; ++mi) af[mi] = *(const bf16x8*)(cA + mi * 16 * LDT + ks * 32);
; #pragma unroll
; template <int EPI>
; __device__ __forceinline__ void gemm_phase(const Params& p, const EpiArgs& ea, const bf16_t* A, int lda, const bf16_t* Bt, int K,
;                            int Mtiles, int Ntiles, int a_mode, int rot, char* smem) {
;     ...
;     int L = (r * nxcd + x) * per + kk;
;     if (L >= ntiles) { if ((r * nxcd) * per >= ntiles) break; else continue; }
;     int band = L / (4 * Ntiles);
;     int rem = L - band * 4 * Ntiles;
;     int bm = Mtiles - band * 4; if (bm > 4) bm = 4;
;     int nt = rem / bm, mi = rem - nt * bm;
;     int mt = band * 4 + mi;
;     const bf16_t* Ap = A;
;     if (a_mode == 1) Ap = A + (nt >> 1) * 128;
;     gemm_tile<EPI>(p, ea, Ap, lda, Bt, K, mt * 256, nt * 128, smem);
.LBB0_150:
	s_add_i32 s4, s7, s8
	s_cmpk_lt_i32 s4, 0x420
	s_mov_b64 s[2:3], -1
	s_cbranch_scc0 .LBB0_282
	s_ashr_i32 s2, s4, 31
	s_lshr_b32 s2, s2, 26
	s_add_i32 s2, s4, s2
	s_ashr_i32 s3, s2, 6
	s_lshl_b32 s5, s3, 2
	s_sub_i32 s5, 0x42, s5
	s_min_u32 s5, s5, 4
	v_cvt_f32_ubyte0_e32 v0, s5
	v_rcp_iflag_f32_e32 v0, v0
	s_andn2_b32 s2, s2, 63
	s_sub_i32 s9, s4, s2
	s_ashr_i32 s9, s9, 31
	v_mul_f32_e32 v0, 0x4f7ffffe, v0
	v_cvt_u32_f32_e32 v0, v0
	s_sub_i32 s10, 0, s5
	s_sub_i32 s2, s9, s2
	s_add_i32 s2, s4, s2
	v_readfirstlane_b32 s11, v0
	s_mul_i32 s10, s10, s11
	s_mul_hi_u32 s10, s11, s10
	s_xor_b32 s2, s2, s9
	s_add_i32 s11, s11, s10
	s_mul_hi_u32 s10, s2, s11
	s_mul_i32 s11, s10, s5
	s_sub_i32 s2, s2, s11
	s_add_i32 s11, s10, 1
	s_sub_i32 s12, s2, s5
	s_cmp_ge_u32 s2, s5
	s_cselect_b32 s10, s11, s10
	s_cselect_b32 s2, s12, s2
	s_add_i32 s11, s10, 1
	s_cmp_ge_u32 s2, s5
	s_cselect_b32 s2, s11, s10
	s_xor_b32 s2, s2, s9
	s_sub_i32 s9, s2, s9
	s_mul_i32 s2, s5, s9
	s_mul_i32 s3, s3, 60
	s_add_i32 s2, s2, s3
	s_sub_i32 s3, s4, s2
	s_lshl_b32 s2, s9, 6
	s_and_b32 s4, s2, 0xffffff80
	s_ashr_i32 s5, s4, 31
	s_lshl_b64 s[4:5], s[4:5], 1
	s_add_u32 s10, s40, s4
	v_mov_b32_e32 v65, v164
	s_addc_u32 s11, s41, s5
	s_lshl_b32 s4, s3, 8
	s_movk_i32 s5, 0x90
	v_ashrrev_i32_e32 v4, 3, v65
	v_add_u32_e32 v0, s4, v4
	v_ashrrev_i32_e32 v1, 31, v0
	v_lshlrev_b64 v[0:1], 11, v[0:1]
	v_lshlrev_b32_e32 v2, 4, v65
	v_lshl_add_u64 v[0:1], s[10:11], 0, v[0:1]
	v_and_b32_e32 v166, 0x70, v2
	v_lshl_add_u64 v[2:3], v[0:1], 0, v[166:167]
	v_lshl_add_u32 v0, s9, 7, v4
	s_waitcnt vmcnt(0)
	v_mul_lo_u32 v112, v4, s5
	global_load_dwordx4 v[120:123], v[2:3], off
	global_load_dwordx4 v[144:147], v[2:3], off offset:128
	v_add3_u32 v113, 0, v166, v112
	s_mov_b32 s3, 0x20000
	v_ashrrev_i32_e32 v1, 31, v0
	v_lshlrev_b64 v[0:1], 8, v[0:1]
	v_lshl_add_u64 v[0:1], s[44:45], 0, v[0:1]
	v_lshl_add_u64 v[0:1], v[0:1], 0, v[166:167]
	global_load_dwordx4 v[136:139], v[0:1], off
	global_load_dwordx4 v[148:151], v[0:1], off offset:128
	v_add_co_u32_e32 v4, vcc, s3, v2
	s_mov_b32 s3, 0x40000
	s_nop 0
	v_addc_co_u32_e32 v5, vcc, 0, v3, vcc
	global_load_dwordx4 v[124:127], v[4:5], off
	global_load_dwordx4 v[152:155], v[4:5], off offset:128
	v_add_co_u32_e32 v6, vcc, s3, v2
	s_mov_b32 s3, 0x60000
	s_nop 0
	v_addc_co_u32_e32 v7, vcc, 0, v3, vcc
	global_load_dwordx4 v[128:131], v[6:7], off
	global_load_dwordx4 v[156:159], v[6:7], off offset:128
	v_add_co_u32_e32 v8, vcc, s3, v2
	s_movk_i32 s3, 0x4000
	s_nop 0
	v_addc_co_u32_e32 v9, vcc, 0, v3, vcc
	global_load_dwordx4 v[132:135], v[8:9], off
	global_load_dwordx4 v[160:163], v[8:9], off offset:128
	v_add_co_u32_e32 v10, vcc, s3, v0
	v_readlane_b32 s3, v255, 30
	s_nop 0
	v_addc_co_u32_e32 v11, vcc, 0, v1, vcc
	global_load_dwordx4 v[140:143], v[10:11], off
	global_load_dwordx4 v[172:175], v[10:11], off offset:128
	v_readlane_b32 s9, v255, 29
	v_bfe_u32 v66, v65, 4, 2
	v_ashrrev_i32_e32 v64, 8, v65
	v_add3_u32 v16, s9, v166, v112
	v_and_b32_e32 v67, 15, v65
	s_waitcnt vmcnt(11)
	ds_write_b128 v113, v[120:123]
	s_waitcnt vmcnt(9)
	ds_write_b128 v16, v[136:139]
	s_waitcnt vmcnt(7)
	ds_write_b128 v113, v[124:127] offset:9216
	s_waitcnt vmcnt(5)
	ds_write_b128 v113, v[128:131] offset:18432
	s_waitcnt vmcnt(3)
	ds_write_b128 v113, v[132:135] offset:27648
	s_waitcnt vmcnt(1)
	ds_write_b128 v16, v[140:143] offset:9216
	v_and_b32_e32 v12, 0xcf, v65
	v_mul_u32_u24_e32 v12, 0x90, v12
	v_lshlrev_b32_e32 v13, 4, v66
	v_add3_u32 v114, 0, v12, v13
	v_lshl_or_b32 v12, v64, 6, v67
	v_mul_lo_u32 v12, v12, s5
	s_waitcnt lgkmcnt(0)
	s_barrier
	v_add3_u32 v116, s9, v12, v13
	ds_read_b128 v[12:15], v114
	ds_read_b128 v[16:19], v114 offset:2304
	ds_read_b128 v[20:23], v114 offset:4608
	ds_read_b128 v[24:27], v114 offset:6912
	ds_read_b128 v[28:31], v116
	ds_read_b128 v[32:35], v116 offset:2304
	ds_read_b128 v[36:39], v116 offset:4608
	ds_read_b128 v[40:43], v116 offset:6912
	s_waitcnt lgkmcnt(3)
	v_mfma_f32_16x16x32_bf16 v[44:47], v[12:15], v[28:31], 0
	v_or_b32_e32 v67, s2, v67
	v_lshl_add_u32 v64, v64, 5, v67
	s_mov_b32 s9, 0xbe99999a
	s_waitcnt lgkmcnt(2)
	v_mfma_f32_16x16x32_bf16 v[48:51], v[12:15], v[32:35], 0
	s_waitcnt lgkmcnt(1)
	v_mfma_f32_16x16x32_bf16 v[52:55], v[12:15], v[36:39], 0
	s_waitcnt lgkmcnt(0)
	v_mfma_f32_16x16x32_bf16 v[12:15], v[12:15], v[40:43], 0
	v_mfma_f32_16x16x32_bf16 v[56:59], v[16:19], v[28:31], 0
	v_mfma_f32_16x16x32_bf16 v[60:63], v[16:19], v[32:35], 0
	v_mfma_f32_16x16x32_bf16 v[68:71], v[16:19], v[36:39], 0
	v_mfma_f32_16x16x32_bf16 v[16:19], v[16:19], v[40:43], 0
	v_mfma_f32_16x16x32_bf16 v[72:75], v[20:23], v[28:31], 0
	v_mfma_f32_16x16x32_bf16 v[76:79], v[20:23], v[32:35], 0
	v_mfma_f32_16x16x32_bf16 v[80:83], v[20:23], v[36:39], 0
	v_mfma_f32_16x16x32_bf16 v[20:23], v[20:23], v[40:43], 0
	v_mfma_f32_16x16x32_bf16 v[28:31], v[24:27], v[28:31], 0
	v_mfma_f32_16x16x32_bf16 v[32:35], v[24:27], v[32:35], 0
	v_mfma_f32_16x16x32_bf16 v[36:39], v[24:27], v[36:39], 0
	v_mfma_f32_16x16x32_bf16 v[24:27], v[24:27], v[40:43], 0
	ds_read_b128 v[40:43], v114 offset:64
	ds_read_b128 v[84:87], v114 offset:2368
	ds_read_b128 v[88:91], v114 offset:4672
	ds_read_b128 v[92:95], v114 offset:6976
	ds_read_b128 v[96:99], v116 offset:64
	ds_read_b128 v[100:103], v116 offset:2368
	ds_read_b128 v[104:107], v116 offset:4672
	ds_read_b128 v[108:111], v116 offset:6976
	s_waitcnt lgkmcnt(3)
	v_mfma_f32_16x16x32_bf16 v[44:47], v[40:43], v[96:99], v[44:47]
	s_waitcnt lgkmcnt(2)
	v_mfma_f32_16x16x32_bf16 v[48:51], v[40:43], v[100:103], v[48:51]
	s_waitcnt lgkmcnt(1)
	v_mfma_f32_16x16x32_bf16 v[52:55], v[40:43], v[104:107], v[52:55]
	s_waitcnt lgkmcnt(0)
	v_mfma_f32_16x16x32_bf16 v[12:15], v[40:43], v[108:111], v[12:15]
	v_mfma_f32_16x16x32_bf16 v[40:43], v[84:87], v[96:99], v[56:59]
	v_mfma_f32_16x16x32_bf16 v[56:59], v[84:87], v[100:103], v[60:63]
	v_mfma_f32_16x16x32_bf16 v[60:63], v[84:87], v[104:107], v[68:71]
	v_mfma_f32_16x16x32_bf16 v[68:71], v[88:91], v[96:99], v[72:75]
	v_mfma_f32_16x16x32_bf16 v[72:75], v[88:91], v[100:103], v[76:79]
	v_mfma_f32_16x16x32_bf16 v[76:79], v[88:91], v[104:107], v[80:83]
	v_mfma_f32_16x16x32_bf16 v[16:19], v[84:87], v[108:111], v[16:19]
	v_add3_u32 v4, s3, v166, v112
	s_waitcnt vmcnt(0)
	ds_write_b128 v113, v[144:147] offset:36864
	v_mfma_f32_16x16x32_bf16 v[20:23], v[88:91], v[108:111], v[20:23]
	ds_write_b128 v4, v[148:151]
	ds_write_b128 v113, v[152:155] offset:46080
	v_mfma_f32_16x16x32_bf16 v[28:31], v[92:95], v[96:99], v[28:31]
	ds_write_b128 v113, v[156:159] offset:55296
	v_mfma_f32_16x16x32_bf16 v[32:35], v[92:95], v[100:103], v[32:35]
	ds_write_b128 v113, v[160:163] offset:64512
	v_mfma_f32_16x16x32_bf16 v[36:39], v[92:95], v[104:107], v[36:39]
	ds_write_b128 v4, v[172:175] offset:9216
	v_mfma_f32_16x16x32_bf16 v[24:27], v[92:95], v[108:111], v[24:27]
	s_waitcnt lgkmcnt(0)
	s_barrier
; #define MFMA16(a, b, c) __builtin_amdgcn_mfma_f32_16x16x32_bf16(a, b, c, 0, 0, 0)
; template <int EPI>
; __device__ __forceinline__ void gemm_tile(const Params& p, const EpiArgs& ea, const bf16_t* __restrict__ A, int lda,
;                                           const bf16_t* __restrict__ Bt, int K, int m0, int n0, char* smem) {
;     ...
;     for (int ks = 0; ks < 2; ++ks) {
;       bf16x8 af[4], bfg[4];
; #pragma unroll
;       for (int mi = 0; mi < 4; ++mi) af[mi] = *(const bf16x8*)(cA + mi * 16 * LDT + ks * 32);
; #pragma unroll
;       for (int ni = 0; ni < 4; ++ni) bfg[ni] = *(const bf16x8*)(cB + ni * 16 * LDT + ks * 32);
; #pragma unroll
;       for (int mi = 0; mi < 4; ++mi)
; #pragma unroll
;         for (int ni = 0; ni < 4; ++ni) acc[mi][ni] = MFMA16(af[mi], bfg[ni], acc[mi][ni]);
;     }
;     if (kt + 1 < nk) {
;       bf16_t* dA = sA + (buf ^ 1) * 256 * LDT;
;       bf16_t* dB = sB + (buf ^ 1) * 128 * LDT;
; #pragma unroll
;       for (int i = 0; i < 4; ++i) *(uint4*)(dA + (srow + i * 64) * LDT + sch) = ra[i];
; #pragma unroll
;       for (int i = 0; i < 2; ++i) *(uint4*)(dB + (srow + i * 64) * LDT + sch) = rb[i];
;     }
;     __syncthreads();
;     ...
;     } else if (EPI == EPI_LRU) {
; #pragma unroll
;       for (int nh = 0; nh < 2; ++nh) {
;         int ch = (n0 >> 1) + wn * 32 + nh * 16 + fr;
;         float ba = p.lru_b_a[ea.dir * 1024 + ch], bx = p.lru_b_x[ea.dir * 1024 + ch];
;         float sp8 = -8.0f * log1pf(__expf(-p.lru_lam[ea.dir * 1024 + ch]));
	ds_read_b128 v[0:3], v114 offset:36864
	ds_read_b128 v[4:7], v114 offset:39168
	ds_read_b128 v[8:11], v114 offset:41472
	ds_read_b128 v[80:83], v114 offset:43776
	ds_read_b128 v[84:87], v116 offset:18432
	ds_read_b128 v[88:91], v116 offset:20736
	ds_read_b128 v[92:95], v116 offset:23040
	ds_read_b128 v[96:99], v116 offset:25344
	s_waitcnt lgkmcnt(3)
	v_mfma_f32_16x16x32_bf16 v[44:47], v[0:3], v[84:87], v[44:47]
	s_waitcnt lgkmcnt(2)
	v_mfma_f32_16x16x32_bf16 v[48:51], v[0:3], v[88:91], v[48:51]
	s_waitcnt lgkmcnt(1)
	v_mfma_f32_16x16x32_bf16 v[52:55], v[0:3], v[92:95], v[52:55]
	s_waitcnt lgkmcnt(0)
	v_mfma_f32_16x16x32_bf16 v[0:3], v[0:3], v[96:99], v[12:15]
	v_mfma_f32_16x16x32_bf16 v[12:15], v[4:7], v[84:87], v[40:43]
	v_mfma_f32_16x16x32_bf16 v[40:43], v[4:7], v[88:91], v[56:59]
	v_mfma_f32_16x16x32_bf16 v[100:103], v[4:7], v[92:95], v[60:63]
	v_mfma_f32_16x16x32_bf16 v[4:7], v[4:7], v[96:99], v[16:19]
	v_mfma_f32_16x16x32_bf16 v[16:19], v[8:11], v[84:87], v[68:71]
	v_mfma_f32_16x16x32_bf16 v[68:71], v[8:11], v[88:91], v[72:75]
	v_mfma_f32_16x16x32_bf16 v[72:75], v[8:11], v[92:95], v[76:79]
	v_mfma_f32_16x16x32_bf16 v[8:11], v[8:11], v[96:99], v[20:23]
	v_mfma_f32_16x16x32_bf16 v[76:79], v[80:83], v[84:87], v[28:31]
	v_mfma_f32_16x16x32_bf16 v[84:87], v[80:83], v[88:91], v[32:35]
	v_mfma_f32_16x16x32_bf16 v[88:91], v[80:83], v[92:95], v[36:39]
	v_mfma_f32_16x16x32_bf16 v[80:83], v[80:83], v[96:99], v[24:27]
	ds_read_b128 v[20:23], v114 offset:36928
	s_nop 1
	ds_read_b128 v[24:27], v114 offset:39232
	ds_read_b128 v[92:95], v114 offset:41536
	ds_read_b128 v[96:99], v114 offset:43840
	ds_read_b128 v[104:107], v116 offset:18496
	ds_read_b128 v[108:111], v116 offset:20800
	ds_read_b128 v[112:115], v116 offset:23104
	ds_read_b128 v[116:119], v116 offset:25408
	s_waitcnt lgkmcnt(0)
	s_barrier
	s_load_dwordx2 s[2:3], s[0:1], 0xc0
	s_load_dwordx4 s[12:15], s[0:1], 0xd0
	v_mfma_f32_16x16x32_bf16 v[60:63], v[20:23], v[104:107], v[44:47]
	v_mfma_f32_16x16x32_bf16 v[44:47], v[24:27], v[104:107], v[12:15]
	v_mfma_f32_16x16x32_bf16 v[40:43], v[24:27], v[108:111], v[40:43]
	v_mfma_f32_16x16x32_bf16 v[36:39], v[24:27], v[112:115], v[100:103]
	v_mfma_f32_16x16x32_bf16 v[32:35], v[24:27], v[116:119], v[4:7]
	v_mfma_f32_16x16x32_bf16 v[24:27], v[92:95], v[108:111], v[68:71]
	s_nop 2
	v_add_u32_e32 v68, s6, v64
	v_ashrrev_i32_e32 v69, 31, v68
	v_lshlrev_b64 v[68:69], 2, v[68:69]
	v_mfma_f32_16x16x32_bf16 v[56:59], v[20:23], v[108:111], v[48:51]
	v_mfma_f32_16x16x32_bf16 v[52:55], v[20:23], v[112:115], v[52:55]
	v_mfma_f32_16x16x32_bf16 v[48:51], v[20:23], v[116:119], v[0:3]
	v_mfma_f32_16x16x32_bf16 v[20:23], v[92:95], v[112:115], v[72:75]
	s_waitcnt lgkmcnt(0)
	s_nop 1
	v_lshl_add_u64 v[72:73], s[14:15], 0, v[68:69]
	global_load_dword v67, v[72:73], off
	v_lshl_add_u64 v[74:75], s[2:3], 0, v[68:69]
	v_mfma_f32_16x16x32_bf16 v[0:3], v[96:99], v[116:119], v[80:83]
	s_mov_b32 s2, 0x3f2aaaab
	s_waitcnt vmcnt(0)
	v_mul_f32_e32 v67, 0xbfb8aa3b, v67
	global_load_dword v83, v[74:75], off
	v_exp_f32_e32 v67, v67
	v_mfma_f32_16x16x32_bf16 v[12:15], v[96:99], v[104:107], v[76:79]
	v_add_f32_e32 v70, 1.0, v67
	s_nop 1
	v_lshl_add_u64 v[76:77], s[12:13], 0, v[68:69]
	v_add_f32_e32 v68, -1.0, v70
	global_load_dword v82, v[76:77], off
	v_sub_f32_e32 v69, v68, v70
	v_add_f32_e32 v69, 1.0, v69
	v_sub_f32_e32 v68, v67, v68
	v_add_f32_e32 v71, v68, v69
	v_frexp_mant_f32_e32 v68, v70
	v_cmp_gt_f32_e32 vcc, s2, v68
	v_cvt_f64_f32_e32 v[68:69], v70
	v_frexp_exp_i32_f64_e32 v68, v[68:69]
	v_mfma_f32_16x16x32_bf16 v[28:31], v[92:95], v[104:107], v[16:19]
	s_mov_b32 s2, 0x3f317218
	s_waitcnt vmcnt(1)
	v_add_f32_e32 v60, v60, v83
	v_mfma_f32_16x16x32_bf16 v[16:19], v[92:95], v[116:119], v[8:11]
	v_mul_f32_e32 v60, 0xbfb8aa3b, v60
	v_exp_f32_e32 v60, v60
	v_mfma_f32_16x16x32_bf16 v[8:11], v[96:99], v[108:111], v[84:87]
	v_add_f32_e32 v60, 1.0, v60
	v_rcp_f32_e32 v60, v60
	s_nop 0
	v_subbrev_co_u32_e32 v84, vcc, 0, v68, vcc
	v_sub_u32_e32 v68, 0, v84
	v_ldexp_f32 v69, v70, v68
	v_add_f32_e32 v70, -1.0, v69
	v_add_f32_e32 v78, 1.0, v69
	v_ldexp_f32 v68, v71, v68
	v_add_f32_e32 v71, 1.0, v70
	v_add_f32_e32 v79, -1.0, v78
	v_sub_f32_e32 v71, v69, v71
	v_sub_f32_e32 v69, v69, v79
	v_add_f32_e32 v71, v68, v71
	v_add_f32_e32 v68, v68, v69
	v_add_f32_e32 v85, v78, v68
	v_rcp_f32_e32 v87, v85
	v_sub_f32_e32 v69, v85, v78
	v_sub_f32_e32 v86, v68, v69
	v_add_f32_e32 v69, v70, v71
	v_mfma_f32_16x16x32_bf16 v[4:7], v[96:99], v[112:115], v[88:91]
	v_sub_f32_e32 v68, v69, v70
	s_nop 1
	v_mul_f32_e32 v89, v69, v87
	v_mul_f32_e32 v70, v85, v89
	v_fma_f32 v78, v89, v85, -v70
	v_fmac_f32_e32 v78, v89, v86
	v_sub_f32_e32 v88, v71, v68
	v_add_f32_e32 v68, v70, v78
	v_sub_f32_e32 v71, v69, v68
	v_pk_add_f32 v[80:81], v[68:69], v[70:71] neg_lo:[0,1] neg_hi:[0,1]
	v_mov_b32_e32 v79, v68
	v_pk_add_f32 v[68:69], v[80:81], v[78:79] neg_lo:[0,1] neg_hi:[0,1]
	s_nop 0
	v_add_f32_e32 v69, v88, v69
	v_add_f32_e32 v68, v68, v69
	v_add_f32_e32 v69, v71, v68
	v_mul_f32_e32 v88, v87, v69
	v_mul_f32_e32 v70, v85, v88
	v_fma_f32 v78, v88, v85, -v70
	v_fmac_f32_e32 v78, v88, v86
	v_sub_f32_e32 v71, v71, v69
	v_add_f32_e32 v85, v68, v71
	v_add_f32_e32 v68, v70, v78
	v_sub_f32_e32 v71, v69, v68
	v_pk_add_f32 v[80:81], v[68:69], v[70:71] neg_lo:[0,1] neg_hi:[0,1]
	v_mov_b32_e32 v79, v68
	v_pk_add_f32 v[68:69], v[80:81], v[78:79] neg_lo:[0,1] neg_hi:[0,1]
	s_nop 0
	v_add_f32_e32 v69, v85, v69
	v_add_f32_e32 v68, v68, v69
	v_add_f32_e32 v69, v89, v88
	v_add_f32_e32 v68, v71, v68
	v_sub_f32_e32 v70, v69, v89
	v_mul_f32_e32 v68, v87, v68
	v_sub_f32_e32 v70, v88, v70
	v_add_f32_e32 v70, v70, v68
	v_add_f32_e32 v78, v69, v70
;   __host__ __device__ __forceinline__ bf16_t* XC() const { return (bf16_t*)(wsl() + OFF_FFN); }
; __device__ __forceinline__ float bf2f(bf16_t h) { return __uint_as_float(((uint32_t)h) << 16); }
; __device__ __forceinline__ uint32_t pack2(float a, float b) { uint32_t r; asm("v_cvt_pk_bf16_f32 %0, %1, %2" : "=v"(r) : "v"(a), "v"(b)); return r; }
; __device__ __forceinline__ float sigmoidf_(float x) { return __builtin_amdgcn_rcpf(1.0f + __expf(-x)); }
; template <int EPI>
; __device__ __forceinline__ void gemm_tile(const Params& p, const EpiArgs& ea, const bf16_t* __restrict__ A, int lda,
;                                           const bf16_t* __restrict__ Bt, int K, int m0, int n0, char* smem) {
;     ...
;         float sp8 = -8.0f * log1pf(__expf(-p.lru_lam[ea.dir * 1024 + ch]));
; #pragma unroll
;         for (int j = 0; j < 4; ++j) {
;           float r = sigmoidf_(acc[mi][nh * 2][j] + ba);
;           float ig = sigmoidf_(acc[mi][nh * 2 + 1][j] + bx);
;           float la = r * sp8;
;           float x2 = 2.0f * la;
;           float poly = -x2 * (1.0f + x2 * (0.5f + x2 * (0.16666667f + x2 * (0.041666668f + x2 * (0.008333334f + x2 * 0.0013888889f)))));
;           float em = (x2 < -0.3f) ? (1.0f - __expf(x2)) : poly;
;           float u = bf2f(p.XC()[(size_t)(r0 + j) * D + ch]);
;           float inp = __builtin_amdgcn_sqrtf(fmaxf(em, 0.0f)) * (ig * u);
;           ea.outu[(size_t)(r0 + j) * D + ch] = pack2(la, inp);
	v_mul_f32_e32 v79, v78, v78
	v_fmamk_f32 v68, v79, 0x3e9b6dac, v165
	v_fmaak_f32 v171, v79, v68, 0x3f2aaada
	v_cvt_f32_i32_e32 v68, v84
	v_sub_f32_e32 v69, v78, v69
	v_sub_f32_e32 v69, v70, v69
	v_ldexp_f32 v80, v69, 1
	v_mul_f32_e32 v69, v78, v79
	v_ldexp_f32 v71, v78, 1
	v_pk_mul_f32 v[78:79], v[68:69], v[170:171]
	s_nop 0
	v_fma_f32 v70, v68, s2, -v78
	v_fmac_f32_e32 v70, 0xb102e308, v68
	v_pk_add_f32 v[68:69], v[78:79], v[70:71]
	s_mov_b32 s2, 0x7f800000
	v_sub_f32_e32 v71, v69, v71
	v_sub_f32_e32 v71, v79, v71
	v_add_f32_e32 v81, v80, v71
	v_mov_b32_e32 v80, v78
	v_pk_add_f32 v[78:79], v[68:69], v[78:79] neg_lo:[0,1] neg_hi:[0,1]
	v_pk_add_f32 v[84:85], v[68:69], v[80:81]
	v_mov_b32_e32 v71, v68
	v_mov_b32_e32 v79, v85
	v_pk_add_f32 v[86:87], v[70:71], v[78:79] neg_lo:[0,1] neg_hi:[0,1]
	v_pk_add_f32 v[70:71], v[70:71], v[78:79]
	v_mov_b32_e32 v80, v81
	v_pk_add_f32 v[78:79], v[70:71], v[68:69] op_sel:[1,0] op_sel_hi:[0,1] neg_lo:[0,1] neg_hi:[0,1]
	v_pk_add_f32 v[88:89], v[84:85], v[78:79] op_sel_hi:[1,0] neg_lo:[0,1] neg_hi:[0,1]
	v_mov_b32_e32 v84, v85
	v_mov_b32_e32 v85, v71
	v_pk_mov_b32 v[78:79], v[68:69], v[78:79] op_sel:[1,0]
	v_mov_b32_e32 v81, v68
	v_pk_add_f32 v[78:79], v[84:85], v[78:79] neg_lo:[0,1] neg_hi:[0,1]
	v_mov_b32_e32 v88, v86
	v_pk_add_f32 v[68:69], v[80:81], v[78:79] neg_lo:[0,1] neg_hi:[0,1]
	v_mov_b32_e32 v87, v71
	v_pk_add_f32 v[78:79], v[88:89], v[68:69]
	v_cmp_neq_f32_e32 vcc, s2, v67
	v_pk_add_f32 v[80:81], v[78:79], v[78:79] op_sel:[0,1] op_sel_hi:[1,0]
	s_mov_b32 s2, 0x33800000
	v_pk_add_f32 v[70:71], v[70:71], v[80:81] op_sel:[1,0] op_sel_hi:[0,1]
	v_mov_b32_e32 v79, v70
	v_pk_add_f32 v[84:85], v[78:79], v[86:87] neg_lo:[0,1] neg_hi:[0,1]
	v_mov_b32_e32 v69, v80
	v_sub_f32_e32 v71, v78, v84
	v_pk_add_f32 v[68:69], v[68:69], v[84:85] neg_lo:[0,1] neg_hi:[0,1]
	v_sub_f32_e32 v71, v86, v71
	v_add_f32_e32 v68, v68, v71
	v_add_f32_e32 v68, v68, v69
	v_add_f32_e32 v68, v70, v68
	v_cndmask_b32_e32 v68, v225, v68, vcc
	v_cmp_ngt_f32_e32 vcc, -1.0, v67
	s_nop 1
	v_cndmask_b32_e32 v68, v226, v68, vcc
	v_cmp_neq_f32_e32 vcc, -1.0, v67
	s_nop 1
	v_cndmask_b32_e32 v68, v227, v68, vcc
	v_cmp_lt_f32_e64 vcc, |v67|, s2
	s_nop 1
	v_cndmask_b32_e32 v67, v68, v67, vcc
	v_mul_f32_e32 v84, 0xc1000000, v67
	v_mul_f32_e32 v60, v60, v84
	v_add_f32_e32 v67, v60, v60
	v_cmp_ngt_f32_e32 vcc, s9, v67
	s_and_saveexec_b64 s[2:3], vcc
	s_xor_b64 s[2:3], exec, s[2:3]
	v_fmamk_f32 v68, v67, 0x3ab60b61, v169
	v_fmaak_f32 v68, v67, v68, 0x3d2aaaab
	v_fmaak_f32 v68, v67, v68, 0x3e2aaaab
	v_fma_f32 v68, v67, v68, 0.5
	v_fma_f32 v68, v67, v68, 1.0
	v_mul_f32_e64 v78, v68, -v67
	s_andn2_saveexec_b64 s[2:3], s[2:3]
	v_mul_f32_e32 v67, 0x3fb8aa3b, v67
	v_exp_f32_e32 v67, v67
	s_nop 0
	v_sub_f32_e32 v78, 1.0, v67
	s_or_b64 exec, exec, s[2:3]
	v_and_b32_e32 v65, 0xc0, v65
	v_lshlrev_b32_e32 v66, 2, v66
	v_or3_b32 v66, v66, v65, s4
	v_and_b32_e32 v121, 0xff, v66
	v_mul_u32_u24_e32 v121, 0x90, v121
	v_and_b32_e32 v122, 63, v64
	v_lshl_add_u32 v121, v122, 1, v121
	v_bfe_u32 v122, v64, 6, 1
	v_mul_u32_u24_e32 v122, 0x9000, v122
	v_add_u32_e32 v120, v121, v122
	v_ashrrev_i32_e32 v67, 31, v66
	v_ashrrev_i32_e32 v65, 31, v64
	v_lshlrev_b64 v[68:69], 10, v[66:67]
	v_lshl_add_u64 v[80:81], v[68:69], 0, v[64:65]
	v_lshl_add_u64 v[70:71], v[80:81], 1, s[40:41]
	ds_read_u16 v67, v120 offset:0
	s_waitcnt vmcnt(0)
	v_add_f32_e32 v56, v56, v82
	v_mul_f32_e32 v56, 0xbfb8aa3b, v56
	v_exp_f32_e32 v56, v56
	v_max_f32_e32 v78, v78, v78
	v_max_f32_e32 v78, 0, v78
	v_sqrt_f32_e32 v78, v78
	v_add_f32_e32 v56, 1.0, v56
	v_rcp_f32_e32 v56, v56
	s_waitcnt lgkmcnt(0)
	v_lshlrev_b32_e32 v67, 16, v67
	v_mul_f32_e32 v56, v56, v67
	v_mul_f32_e32 v56, v78, v56
	v_cvt_pk_bf16_f32 v56, v60, v56
	v_lshl_add_u64 v[78:79], v[80:81], 2, s[42:43]
	global_store_dword v[78:79], v56, off
	v_add_f32_e32 v56, v61, v83
	v_mul_f32_e32 v56, 0xbfb8aa3b, v56
	v_exp_f32_e32 v56, v56
	s_nop 0
	v_add_f32_e32 v56, 1.0, v56
	v_rcp_f32_e32 v56, v56
	s_nop 0
	v_mul_f32_e32 v67, v56, v84
	v_add_f32_e32 v56, v67, v67
	v_cmp_ngt_f32_e32 vcc, s9, v56
	s_and_saveexec_b64 s[2:3], vcc
	s_xor_b64 s[2:3], exec, s[2:3]
	v_fmamk_f32 v60, v56, 0x3ab60b61, v169
	v_fmaak_f32 v60, v56, v60, 0x3d2aaaab
	v_fmaak_f32 v60, v56, v60, 0x3e2aaaab
	v_fma_f32 v60, v56, v60, 0.5
	v_fma_f32 v60, v56, v60, 1.0
	v_mul_f32_e64 v78, v60, -v56
	s_andn2_saveexec_b64 s[2:3], s[2:3]
	v_mul_f32_e32 v56, 0x3fb8aa3b, v56
	v_exp_f32_e32 v56, v56
	s_nop 0
	v_sub_f32_e32 v78, 1.0, v56
	s_or_b64 exec, exec, s[2:3]
	v_add_f32_e32 v56, v57, v82
	v_mul_f32_e32 v56, 0xbfb8aa3b, v56
	v_exp_f32_e32 v56, v56
	v_add_f32_e32 v62, v62, v83
	v_mul_f32_e32 v62, 0xbfb8aa3b, v62
	v_exp_f32_e32 v62, v62
	v_add_f32_e32 v56, 1.0, v56
	v_rcp_f32_e32 v79, v56
	v_or_b32_e32 v56, 1, v66
	v_ashrrev_i32_e32 v57, 31, v56
	v_lshlrev_b64 v[56:57], 10, v[56:57]
	v_lshl_add_u64 v[80:81], v[56:57], 0, v[64:65]
	v_lshl_add_u64 v[60:61], v[80:81], 1, s[40:41]
	ds_read_u16 v85, v120 offset:144
	v_max_f32_e32 v78, v78, v78
	v_max_f32_e32 v78, 0, v78
	v_sqrt_f32_e32 v78, v78
	v_add_f32_e32 v62, 1.0, v62
	v_rcp_f32_e32 v62, v62
	s_waitcnt lgkmcnt(0)
;   __host__ __device__ __forceinline__ bf16_t* XC() const { return (bf16_t*)(wsl() + OFF_FFN); }
; __device__ __forceinline__ float bf2f(bf16_t h) { return __uint_as_float(((uint32_t)h) << 16); }
; __device__ __forceinline__ uint32_t pack2(float a, float b) { uint32_t r; asm("v_cvt_pk_bf16_f32 %0, %1, %2" : "=v"(r) : "v"(a), "v"(b)); return r; }
; __device__ __forceinline__ float sigmoidf_(float x) { return __builtin_amdgcn_rcpf(1.0f + __expf(-x)); }
; template <int EPI>
; __device__ __forceinline__ void gemm_tile(const Params& p, const EpiArgs& ea, const bf16_t* __restrict__ A, int lda,
;                                           const bf16_t* __restrict__ Bt, int K, int m0, int n0, char* smem) {
;     ...
;         int ch = (n0 >> 1) + wn * 32 + nh * 16 + fr;
;         float ba = p.lru_b_a[ea.dir * 1024 + ch], bx = p.lru_b_x[ea.dir * 1024 + ch];
;         float sp8 = -8.0f * log1pf(__expf(-p.lru_lam[ea.dir * 1024 + ch]));
;     ...
;         for (int j = 0; j < 4; ++j) {
;           float r = sigmoidf_(acc[mi][nh * 2][j] + ba);
;           float ig = sigmoidf_(acc[mi][nh * 2 + 1][j] + bx);
;           float la = r * sp8;
;           float x2 = 2.0f * la;
;           float poly = -x2 * (1.0f + x2 * (0.5f + x2 * (0.16666667f + x2 * (0.041666668f + x2 * (0.008333334f + x2 * 0.0013888889f)))));
;           float em = (x2 < -0.3f) ? (1.0f - __expf(x2)) : poly;
;           float u = bf2f(p.XC()[(size_t)(r0 + j) * D + ch]);
;           float inp = __builtin_amdgcn_sqrtf(fmaxf(em, 0.0f)) * (ig * u);
;           ea.outu[(size_t)(r0 + j) * D + ch] = pack2(la, inp);
	v_lshlrev_b32_e32 v85, 16, v85
	v_mul_f32_e32 v79, v79, v85
	v_mul_f32_e32 v78, v78, v79
	v_cvt_pk_bf16_f32 v67, v67, v78
	v_lshl_add_u64 v[78:79], v[80:81], 2, s[42:43]
	v_mul_f32_e32 v62, v62, v84
	global_store_dword v[78:79], v67, off
	v_add_f32_e32 v67, v62, v62
	v_cmp_ngt_f32_e32 vcc, s9, v67
	s_and_saveexec_b64 s[2:3], vcc
	s_xor_b64 s[2:3], exec, s[2:3]
	v_fmamk_f32 v78, v67, 0x3ab60b61, v169
	v_fmaak_f32 v78, v67, v78, 0x3d2aaaab
	v_fmaak_f32 v78, v67, v78, 0x3e2aaaab
	v_fma_f32 v78, v67, v78, 0.5
	v_fma_f32 v78, v67, v78, 1.0
	v_mul_f32_e64 v85, v78, -v67
	s_andn2_saveexec_b64 s[2:3], s[2:3]
	v_mul_f32_e32 v67, 0x3fb8aa3b, v67
	v_exp_f32_e32 v67, v67
	s_nop 0
	v_sub_f32_e32 v85, 1.0, v67
	s_or_b64 exec, exec, s[2:3]
	v_or_b32_e32 v78, 2, v66
	v_ashrrev_i32_e32 v79, 31, v78
	v_lshlrev_b64 v[78:79], 10, v[78:79]
	v_lshl_add_u64 v[86:87], v[78:79], 0, v[64:65]
	v_lshl_add_u64 v[80:81], v[86:87], 1, s[40:41]
	ds_read_u16 v88, v120 offset:288
	v_add_f32_e32 v63, v63, v83
	v_mul_f32_e32 v63, 0xbfb8aa3b, v63
	v_add_f32_e32 v58, v58, v82
	v_exp_f32_e32 v63, v63
	v_mul_f32_e32 v58, 0xbfb8aa3b, v58
	v_exp_f32_e32 v58, v58
	v_max_f32_e32 v67, v85, v85
	v_add_f32_e32 v63, 1.0, v63
	v_rcp_f32_e32 v63, v63
	v_add_f32_e32 v58, 1.0, v58
	v_max_f32_e32 v67, 0, v67
	v_rcp_f32_e32 v89, v58
	v_sqrt_f32_e32 v85, v67
	v_mul_f32_e32 v67, v63, v84
	v_add_f32_e32 v58, v67, v67
	v_lshl_add_u64 v[86:87], v[86:87], 2, s[42:43]
	v_cmp_ngt_f32_e32 vcc, s9, v58
	s_waitcnt lgkmcnt(0)
	v_lshlrev_b32_e32 v63, 16, v88
	v_mul_f32_e32 v63, v89, v63
	v_mul_f32_e32 v63, v85, v63
	v_cvt_pk_bf16_f32 v62, v62, v63
	global_store_dword v[86:87], v62, off
	s_and_saveexec_b64 s[2:3], vcc
	s_xor_b64 s[2:3], exec, s[2:3]
	v_fmamk_f32 v62, v58, 0x3ab60b61, v169
	v_fmaak_f32 v62, v58, v62, 0x3d2aaaab
	v_fmaak_f32 v62, v58, v62, 0x3e2aaaab
	v_fma_f32 v62, v58, v62, 0.5
	v_fma_f32 v62, v58, v62, 1.0
	v_mul_f32_e64 v85, v62, -v58
	s_andn2_saveexec_b64 s[2:3], s[2:3]
	v_mul_f32_e32 v58, 0x3fb8aa3b, v58
	v_exp_f32_e32 v58, v58
	s_nop 0
	v_sub_f32_e32 v85, 1.0, v58
	s_or_b64 exec, exec, s[2:3]
	v_add_f32_e32 v58, v59, v82
	v_mul_f32_e32 v58, 0xbfb8aa3b, v58
	v_exp_f32_e32 v58, v58
	v_max_f32_e32 v85, v85, v85
	v_max_f32_e32 v85, 0, v85
	v_sqrt_f32_e32 v85, v85
	v_add_f32_e32 v58, 1.0, v58
	v_rcp_f32_e32 v88, v58
	v_or_b32_e32 v58, 3, v66
	v_ashrrev_i32_e32 v59, 31, v58
	v_lshlrev_b64 v[58:59], 10, v[58:59]
	v_lshl_add_u64 v[86:87], v[58:59], 0, v[64:65]
	v_lshl_add_u64 v[62:63], v[86:87], 1, s[40:41]
	ds_read_u16 v89, v120 offset:432
	v_lshl_add_u64 v[86:87], v[86:87], 2, s[42:43]
	s_mov_b32 s2, 0x3f2aaaab
	s_waitcnt lgkmcnt(0)
	v_lshlrev_b32_e32 v89, 16, v89
	v_mul_f32_e32 v88, v88, v89
	v_mul_f32_e32 v85, v85, v88
	v_cvt_pk_bf16_f32 v67, v67, v85
	global_store_dword v[86:87], v67, off
	global_load_dword v74, v[74:75], off offset:64
	s_nop 0
	global_load_dword v67, v[76:77], off offset:64
	s_nop 0
	global_load_dword v72, v[72:73], off offset:64
	s_waitcnt vmcnt(2)
	v_add_f32_e32 v52, v52, v74
	v_mul_f32_e32 v52, 0xbfb8aa3b, v52
	s_waitcnt vmcnt(0)
	v_mul_f32_e32 v72, 0xbfb8aa3b, v72
	v_exp_f32_e32 v75, v72
	v_exp_f32_e32 v52, v52
	v_add_f32_e32 v76, 1.0, v75
	v_add_f32_e32 v72, -1.0, v76
	v_sub_f32_e32 v73, v72, v76
	v_add_f32_e32 v73, 1.0, v73
	v_sub_f32_e32 v72, v75, v72
	v_add_f32_e32 v77, v72, v73
	v_frexp_mant_f32_e32 v72, v76
	v_cmp_gt_f32_e32 vcc, s2, v72
	v_cvt_f64_f32_e32 v[72:73], v76
	v_frexp_exp_i32_f64_e32 v72, v[72:73]
	v_subbrev_co_u32_e32 v85, vcc, 0, v72, vcc
	v_sub_u32_e32 v72, 0, v85
	v_ldexp_f32 v73, v76, v72
	v_add_f32_e32 v76, -1.0, v73
	v_add_f32_e32 v86, 1.0, v73
	v_ldexp_f32 v72, v77, v72
	v_add_f32_e32 v77, 1.0, v76
	v_add_f32_e32 v87, -1.0, v86
	v_sub_f32_e32 v77, v73, v77
	v_sub_f32_e32 v73, v73, v87
	v_add_f32_e32 v77, v72, v77
	v_add_f32_e32 v72, v72, v73
	v_add_f32_e32 v90, v86, v72
	v_rcp_f32_e32 v92, v90
	v_sub_f32_e32 v73, v90, v86
	v_sub_f32_e32 v91, v72, v73
	v_add_f32_e32 v73, v76, v77
	v_mul_f32_e32 v94, v73, v92
	v_sub_f32_e32 v72, v73, v76
	v_mul_f32_e32 v76, v90, v94
	v_fma_f32 v86, v94, v90, -v76
	v_fmac_f32_e32 v86, v94, v91
	v_sub_f32_e32 v93, v77, v72
	v_add_f32_e32 v72, v76, v86
	v_sub_f32_e32 v77, v73, v72
	v_pk_add_f32 v[88:89], v[72:73], v[76:77] neg_lo:[0,1] neg_hi:[0,1]
	v_mov_b32_e32 v87, v72
	v_pk_add_f32 v[72:73], v[88:89], v[86:87] neg_lo:[0,1] neg_hi:[0,1]
	s_mov_b32 s2, 0x3f317218
	v_add_f32_e32 v73, v93, v73
	v_add_f32_e32 v72, v72, v73
	v_add_f32_e32 v73, v77, v72
	v_mul_f32_e32 v93, v92, v73
	v_mul_f32_e32 v76, v90, v93
	v_fma_f32 v86, v93, v90, -v76
	v_fmac_f32_e32 v86, v93, v91
	v_sub_f32_e32 v77, v77, v73
	v_add_f32_e32 v90, v72, v77
	v_add_f32_e32 v72, v76, v86
	v_sub_f32_e32 v77, v73, v72
	v_pk_add_f32 v[88:89], v[72:73], v[76:77] neg_lo:[0,1] neg_hi:[0,1]
	v_mov_b32_e32 v87, v72
	v_pk_add_f32 v[72:73], v[88:89], v[86:87] neg_lo:[0,1] neg_hi:[0,1]
	v_add_f32_e32 v52, 1.0, v52
	v_add_f32_e32 v73, v90, v73
	v_add_f32_e32 v72, v72, v73
	v_add_f32_e32 v73, v94, v93
	v_add_f32_e32 v72, v77, v72
	v_sub_f32_e32 v76, v73, v94
	v_mul_f32_e32 v72, v92, v72
	v_sub_f32_e32 v76, v93, v76
	v_add_f32_e32 v76, v76, v72
	v_add_f32_e32 v86, v73, v76
	v_mul_f32_e32 v87, v86, v86
	v_fmamk_f32 v72, v87, 0x3e9b6dac, v165
	v_fmaak_f32 v171, v87, v72, 0x3f2aaada
	v_cvt_f32_i32_e32 v72, v85
	v_sub_f32_e32 v73, v86, v73
	v_sub_f32_e32 v73, v76, v73
	v_ldexp_f32 v85, v73, 1
	v_mul_f32_e32 v73, v86, v87
	v_ldexp_f32 v77, v86, 1
	v_pk_mul_f32 v[86:87], v[72:73], v[170:171]
	v_rcp_f32_e32 v52, v52
	v_fma_f32 v76, v72, s2, -v86
	v_fmac_f32_e32 v76, 0xb102e308, v72
	v_pk_add_f32 v[72:73], v[86:87], v[76:77]
	v_mov_b32_e32 v88, v86
	v_sub_f32_e32 v77, v73, v77
;   __host__ __device__ __forceinline__ bf16_t* XC() const { return (bf16_t*)(wsl() + OFF_FFN); }
; __device__ __forceinline__ float bf2f(bf16_t h) { return __uint_as_float(((uint32_t)h) << 16); }
; __device__ __forceinline__ uint32_t pack2(float a, float b) { uint32_t r; asm("v_cvt_pk_bf16_f32 %0, %1, %2" : "=v"(r) : "v"(a), "v"(b)); return r; }
; __device__ __forceinline__ float sigmoidf_(float x) { return __builtin_amdgcn_rcpf(1.0f + __expf(-x)); }
; template <int EPI>
; __device__ __forceinline__ void gemm_tile(const Params& p, const EpiArgs& ea, const bf16_t* __restrict__ A, int lda,
;                                           const bf16_t* __restrict__ Bt, int K, int m0, int n0, char* smem) {
;     ...
;         for (int j = 0; j < 4; ++j) {
;           float r = sigmoidf_(acc[mi][nh * 2][j] + ba);
;           float ig = sigmoidf_(acc[mi][nh * 2 + 1][j] + bx);
;           float la = r * sp8;
;           float x2 = 2.0f * la;
;           float poly = -x2 * (1.0f + x2 * (0.5f + x2 * (0.16666667f + x2 * (0.041666668f + x2 * (0.008333334f + x2 * 0.0013888889f)))));
;           float em = (x2 < -0.3f) ? (1.0f - __expf(x2)) : poly;
;           float u = bf2f(p.XC()[(size_t)(r0 + j) * D + ch]);
;           float inp = __builtin_amdgcn_sqrtf(fmaxf(em, 0.0f)) * (ig * u);
;           ea.outu[(size_t)(r0 + j) * D + ch] = pack2(la, inp);
	v_sub_f32_e32 v77, v87, v77
	v_add_f32_e32 v89, v85, v77
	v_pk_add_f32 v[86:87], v[72:73], v[86:87] neg_lo:[0,1] neg_hi:[0,1]
	v_pk_add_f32 v[90:91], v[72:73], v[88:89]
	v_mov_b32_e32 v77, v72
	v_mov_b32_e32 v87, v91
	v_pk_add_f32 v[92:93], v[76:77], v[86:87] neg_lo:[0,1] neg_hi:[0,1]
	v_pk_add_f32 v[76:77], v[76:77], v[86:87]
	v_mov_b32_e32 v88, v89
	v_pk_add_f32 v[86:87], v[76:77], v[72:73] op_sel:[1,0] op_sel_hi:[0,1] neg_lo:[0,1] neg_hi:[0,1]
	v_pk_add_f32 v[94:95], v[90:91], v[86:87] op_sel_hi:[1,0] neg_lo:[0,1] neg_hi:[0,1]
	v_mov_b32_e32 v90, v91
	v_mov_b32_e32 v91, v77
	v_pk_mov_b32 v[86:87], v[72:73], v[86:87] op_sel:[1,0]
	v_mov_b32_e32 v89, v72
	v_pk_add_f32 v[86:87], v[90:91], v[86:87] neg_lo:[0,1] neg_hi:[0,1]
	v_mov_b32_e32 v94, v92
	v_pk_add_f32 v[72:73], v[88:89], v[86:87] neg_lo:[0,1] neg_hi:[0,1]
	v_mov_b32_e32 v93, v77
	v_pk_add_f32 v[86:87], v[94:95], v[72:73]
	s_mov_b32 s2, 0x7f800000
	v_pk_add_f32 v[88:89], v[86:87], v[86:87] op_sel:[0,1] op_sel_hi:[1,0]
	v_cmp_neq_f32_e32 vcc, s2, v75
	v_pk_add_f32 v[76:77], v[76:77], v[88:89] op_sel:[1,0] op_sel_hi:[0,1]
	v_mov_b32_e32 v87, v76
	v_pk_add_f32 v[90:91], v[86:87], v[92:93] neg_lo:[0,1] neg_hi:[0,1]
	v_mov_b32_e32 v73, v88
	v_sub_f32_e32 v77, v86, v90
	v_pk_add_f32 v[72:73], v[72:73], v[90:91] neg_lo:[0,1] neg_hi:[0,1]
	v_sub_f32_e32 v77, v92, v77
	v_add_f32_e32 v72, v72, v77
	v_add_f32_e32 v72, v72, v73
	v_add_f32_e32 v72, v76, v72
	v_cndmask_b32_e32 v72, v225, v72, vcc
	v_cmp_ngt_f32_e32 vcc, -1.0, v75
	s_mov_b32 s2, 0x33800000
	s_nop 0
	v_cndmask_b32_e32 v72, v226, v72, vcc
	v_cmp_neq_f32_e32 vcc, -1.0, v75
	s_nop 1
	v_cndmask_b32_e32 v72, v227, v72, vcc
	v_cmp_lt_f32_e64 vcc, |v75|, s2
	s_nop 1
	v_cndmask_b32_e32 v72, v72, v75, vcc
	v_mul_f32_e32 v72, 0xc1000000, v72
	v_mul_f32_e32 v73, v52, v72
	v_add_f32_e32 v52, v73, v73
	v_cmp_ngt_f32_e32 vcc, s9, v52
	s_and_saveexec_b64 s[2:3], vcc
	s_xor_b64 s[2:3], exec, s[2:3]
	v_fmamk_f32 v75, v52, 0x3ab60b61, v169
	v_fmaak_f32 v75, v52, v75, 0x3d2aaaab
	v_fmaak_f32 v75, v52, v75, 0x3e2aaaab
	v_fma_f32 v75, v52, v75, 0.5
	v_fma_f32 v75, v52, v75, 1.0
	v_mul_f32_e64 v75, v75, -v52
	s_andn2_saveexec_b64 s[2:3], s[2:3]
	v_mul_f32_e32 v52, 0x3fb8aa3b, v52
	v_exp_f32_e32 v52, v52
	s_nop 0
	v_sub_f32_e32 v75, 1.0, v52
	s_or_b64 exec, exec, s[2:3]
	ds_read_u16 v76, v120 offset:32
	v_add_f32_e32 v48, v48, v67
	v_add_f32_e32 v71, v53, v74
	v_mul_f32_e32 v48, 0xbfb8aa3b, v48
	v_mul_f32_e32 v71, 0xbfb8aa3b, v71
	v_exp_f32_e32 v71, v71
	v_exp_f32_e32 v48, v48
	v_or_b32_e32 v52, 16, v64
	v_max_f32_e32 v70, v75, v75
	v_ashrrev_i32_e32 v53, 31, v52
	v_max_f32_e32 v70, 0, v70
	v_lshl_add_u64 v[68:69], v[68:69], 0, v[52:53]
	v_sqrt_f32_e32 v75, v70
	v_add_f32_e32 v70, 1.0, v71
	v_add_f32_e32 v48, 1.0, v48
	v_rcp_f32_e32 v77, v70
	v_lshl_add_u64 v[70:71], v[68:69], 2, s[42:43]
	v_rcp_f32_e32 v68, v48
	v_mul_f32_e32 v48, v77, v72
	v_add_f32_e32 v69, v48, v48
	v_cmp_ngt_f32_e32 vcc, s9, v69
	s_waitcnt lgkmcnt(0)
	v_lshlrev_b32_e32 v76, 16, v76
	v_mul_f32_e32 v68, v68, v76
	v_mul_f32_e32 v68, v75, v68
	v_cvt_pk_bf16_f32 v68, v73, v68
	global_store_dword v[70:71], v68, off
	s_and_saveexec_b64 s[2:3], vcc
	s_xor_b64 s[2:3], exec, s[2:3]
	v_fmamk_f32 v68, v69, 0x3ab60b61, v169
	v_fmaak_f32 v68, v69, v68, 0x3d2aaaab
	v_fmaak_f32 v68, v69, v68, 0x3e2aaaab
	v_fma_f32 v68, v69, v68, 0.5
	v_fma_f32 v68, v69, v68, 1.0
	v_mul_f32_e64 v68, v68, -v69
	s_andn2_saveexec_b64 s[2:3], s[2:3]
	v_mul_f32_e32 v68, 0x3fb8aa3b, v69
	v_exp_f32_e32 v68, v68
	s_nop 0
	v_sub_f32_e32 v68, 1.0, v68
	s_or_b64 exec, exec, s[2:3]
	ds_read_u16 v60, v120 offset:176
	v_add_f32_e32 v54, v54, v74
	v_add_f32_e32 v49, v49, v67
	v_mul_f32_e32 v54, 0xbfb8aa3b, v54
	v_mul_f32_e32 v49, 0xbfb8aa3b, v49
	v_exp_f32_e32 v54, v54
	v_exp_f32_e32 v49, v49
	v_max_f32_e32 v61, v68, v68
	v_max_f32_e32 v61, 0, v61
	v_add_f32_e32 v54, 1.0, v54
	v_rcp_f32_e32 v54, v54
	v_add_f32_e32 v49, 1.0, v49
	v_rcp_f32_e32 v68, v49
	v_sqrt_f32_e32 v61, v61
	v_mul_f32_e32 v49, v54, v72
	v_lshl_add_u64 v[56:57], v[56:57], 0, v[52:53]
	v_add_f32_e32 v54, v49, v49
	v_lshl_add_u64 v[56:57], v[56:57], 2, s[42:43]
	v_cmp_ngt_f32_e32 vcc, s9, v54
	s_waitcnt lgkmcnt(0)
	v_lshlrev_b32_e32 v60, 16, v60
	v_mul_f32_e32 v60, v68, v60
	v_mul_f32_e32 v60, v61, v60
	v_cvt_pk_bf16_f32 v48, v48, v60
	global_store_dword v[56:57], v48, off
	s_and_saveexec_b64 s[2:3], vcc
	s_xor_b64 s[2:3], exec, s[2:3]
	v_fmamk_f32 v48, v54, 0x3ab60b61, v169
	v_fmaak_f32 v48, v54, v48, 0x3d2aaaab
	v_fmaak_f32 v48, v54, v48, 0x3e2aaaab
	v_fma_f32 v48, v54, v48, 0.5
	v_fma_f32 v48, v54, v48, 1.0
	v_mul_f32_e64 v48, v48, -v54
	s_andn2_saveexec_b64 s[2:3], s[2:3]
	v_mul_f32_e32 v48, 0x3fb8aa3b, v54
	v_exp_f32_e32 v48, v48
	s_nop 0
	v_sub_f32_e32 v48, 1.0, v48
	s_or_b64 exec, exec, s[2:3]
	ds_read_u16 v60, v120 offset:320
	v_add_f32_e32 v54, v55, v74
	v_add_f32_e32 v50, v50, v67
	v_mul_f32_e32 v54, 0xbfb8aa3b, v54
	v_mul_f32_e32 v50, 0xbfb8aa3b, v50
	v_exp_f32_e32 v61, v54
	v_exp_f32_e32 v50, v50
	v_lshl_add_u64 v[56:57], v[78:79], 0, v[52:53]
	v_max_f32_e32 v48, v48, v48
	v_max_f32_e32 v48, 0, v48
	v_lshl_add_u64 v[54:55], v[56:57], 2, s[42:43]
	v_add_f32_e32 v56, 1.0, v61
	v_rcp_f32_e32 v56, v56
	v_sqrt_f32_e32 v57, v48
	v_add_f32_e32 v48, 1.0, v50
	v_rcp_f32_e32 v61, v48
	v_mul_f32_e32 v48, v56, v72
	v_add_f32_e32 v50, v48, v48
	v_cmp_ngt_f32_e32 vcc, s9, v50
	s_waitcnt lgkmcnt(0)
;   __host__ __device__ __forceinline__ bf16_t* XC() const { return (bf16_t*)(wsl() + OFF_FFN); }
; __device__ __forceinline__ float bf2f(bf16_t h) { return __uint_as_float(((uint32_t)h) << 16); }
; __device__ __forceinline__ uint32_t pack2(float a, float b) { uint32_t r; asm("v_cvt_pk_bf16_f32 %0, %1, %2" : "=v"(r) : "v"(a), "v"(b)); return r; }
; __device__ __forceinline__ float sigmoidf_(float x) { return __builtin_amdgcn_rcpf(1.0f + __expf(-x)); }
; template <int EPI>
; __device__ __forceinline__ void gemm_tile(const Params& p, const EpiArgs& ea, const bf16_t* __restrict__ A, int lda,
;                                           const bf16_t* __restrict__ Bt, int K, int m0, int n0, char* smem) {
;     ...
;         for (int j = 0; j < 4; ++j) {
;           float r = sigmoidf_(acc[mi][nh * 2][j] + ba);
;           float ig = sigmoidf_(acc[mi][nh * 2 + 1][j] + bx);
;           float la = r * sp8;
;           float x2 = 2.0f * la;
;           float poly = -x2 * (1.0f + x2 * (0.5f + x2 * (0.16666667f + x2 * (0.041666668f + x2 * (0.008333334f + x2 * 0.0013888889f)))));
;           float em = (x2 < -0.3f) ? (1.0f - __expf(x2)) : poly;
;           float u = bf2f(p.XC()[(size_t)(r0 + j) * D + ch]);
;           float inp = __builtin_amdgcn_sqrtf(fmaxf(em, 0.0f)) * (ig * u);
;           ea.outu[(size_t)(r0 + j) * D + ch] = pack2(la, inp);
	v_lshlrev_b32_e32 v56, 16, v60
	v_mul_f32_e32 v56, v61, v56
	v_mul_f32_e32 v56, v57, v56
	v_cvt_pk_bf16_f32 v49, v49, v56
	global_store_dword v[54:55], v49, off
	s_and_saveexec_b64 s[2:3], vcc
	s_xor_b64 s[2:3], exec, s[2:3]
	v_fmamk_f32 v49, v50, 0x3ab60b61, v169
	v_fmaak_f32 v49, v50, v49, 0x3d2aaaab
	v_fmaak_f32 v49, v50, v49, 0x3e2aaaab
	v_fma_f32 v49, v50, v49, 0.5
	v_fma_f32 v49, v50, v49, 1.0
	v_mul_f32_e64 v49, v49, -v50
	s_andn2_saveexec_b64 s[2:3], s[2:3]
	v_mul_f32_e32 v49, 0x3fb8aa3b, v50
	v_exp_f32_e32 v49, v49
	s_nop 0
	v_sub_f32_e32 v49, 1.0, v49
	s_or_b64 exec, exec, s[2:3]
	ds_read_u16 v54, v120 offset:464
	v_add_f32_e32 v44, v44, v83
	v_add_f32_e32 v55, v51, v67
	v_mul_f32_e32 v44, 0xbfb8aa3b, v44
	v_mul_f32_e32 v55, 0xbfb8aa3b, v55
	v_exp_f32_e32 v44, v44
	v_exp_f32_e32 v55, v55
	v_max_f32_e32 v49, v49, v49
	v_max_f32_e32 v49, 0, v49
	v_add_f32_e32 v44, 1.0, v44
	v_rcp_f32_e32 v44, v44
	v_sqrt_f32_e32 v56, v49
	v_add_f32_e32 v49, 1.0, v55
	v_rcp_f32_e32 v55, v49
	v_mul_f32_e32 v44, v44, v84
	v_lshl_add_u64 v[50:51], v[58:59], 0, v[52:53]
	v_add_f32_e32 v49, v44, v44
	v_lshl_add_u64 v[50:51], v[50:51], 2, s[42:43]
	v_cmp_ngt_f32_e32 vcc, s9, v49
	s_waitcnt lgkmcnt(0)
	v_lshlrev_b32_e32 v54, 16, v54
	v_mul_f32_e32 v54, v55, v54
	v_mul_f32_e32 v54, v56, v54
	v_cvt_pk_bf16_f32 v48, v48, v54
	global_store_dword v[50:51], v48, off
	s_and_saveexec_b64 s[2:3], vcc
	s_xor_b64 s[2:3], exec, s[2:3]
	v_fmamk_f32 v48, v49, 0x3ab60b61, v169
	v_fmaak_f32 v48, v49, v48, 0x3d2aaaab
	v_fmaak_f32 v48, v49, v48, 0x3e2aaaab
	v_fma_f32 v48, v49, v48, 0.5
	v_fma_f32 v48, v49, v48, 1.0
	v_mul_f32_e64 v54, v48, -v49
	s_andn2_saveexec_b64 s[2:3], s[2:3]
	v_mul_f32_e32 v48, 0x3fb8aa3b, v49
	v_exp_f32_e32 v48, v48
	s_nop 0
	v_sub_f32_e32 v54, 1.0, v48
	s_or_b64 exec, exec, s[2:3]
	v_or_b32_e32 v48, 16, v66
	v_ashrrev_i32_e32 v49, 31, v48
	v_lshlrev_b64 v[48:49], 10, v[48:49]
	v_lshl_add_u64 v[56:57], v[48:49], 0, v[64:65]
	v_lshl_add_u64 v[50:51], v[56:57], 1, s[40:41]
	ds_read_u16 v55, v120 offset:2304
	v_add_f32_e32 v40, v40, v82
	v_mul_f32_e32 v40, 0xbfb8aa3b, v40
	v_exp_f32_e32 v40, v40
	v_max_f32_e32 v54, v54, v54
	v_max_f32_e32 v54, 0, v54
	v_sqrt_f32_e32 v54, v54
	v_add_f32_e32 v40, 1.0, v40
	v_rcp_f32_e32 v40, v40
	s_waitcnt lgkmcnt(0)
	v_lshlrev_b32_e32 v55, 16, v55
	v_mul_f32_e32 v40, v40, v55
	v_mul_f32_e32 v40, v54, v40
	v_cvt_pk_bf16_f32 v40, v44, v40
	v_lshl_add_u64 v[54:55], v[56:57], 2, s[42:43]
	global_store_dword v[54:55], v40, off
	v_add_f32_e32 v40, v45, v83
	v_mul_f32_e32 v40, 0xbfb8aa3b, v40
	v_exp_f32_e32 v40, v40
	s_nop 0
	v_add_f32_e32 v40, 1.0, v40
	v_rcp_f32_e32 v40, v40
	s_nop 0
	v_mul_f32_e32 v54, v40, v84
	v_add_f32_e32 v40, v54, v54
	v_cmp_ngt_f32_e32 vcc, s9, v40
	s_and_saveexec_b64 s[2:3], vcc
	s_xor_b64 s[2:3], exec, s[2:3]
	v_fmamk_f32 v44, v40, 0x3ab60b61, v169
	v_fmaak_f32 v44, v40, v44, 0x3d2aaaab
	v_fmaak_f32 v44, v40, v44, 0x3e2aaaab
	v_fma_f32 v44, v40, v44, 0.5
	v_fma_f32 v44, v40, v44, 1.0
	v_mul_f32_e64 v55, v44, -v40
	s_andn2_saveexec_b64 s[2:3], s[2:3]
	v_mul_f32_e32 v40, 0x3fb8aa3b, v40
	v_exp_f32_e32 v40, v40
	s_nop 0
	v_sub_f32_e32 v55, 1.0, v40
	s_or_b64 exec, exec, s[2:3]
	v_add_f32_e32 v40, v41, v82
	v_mul_f32_e32 v40, 0xbfb8aa3b, v40
	v_exp_f32_e32 v40, v40
	v_add_f32_e32 v46, v46, v83
	v_mul_f32_e32 v46, 0xbfb8aa3b, v46
	v_exp_f32_e32 v46, v46
	v_add_f32_e32 v40, 1.0, v40
	v_rcp_f32_e32 v58, v40
	v_or_b32_e32 v40, 17, v66
	v_ashrrev_i32_e32 v41, 31, v40
	v_lshlrev_b64 v[40:41], 10, v[40:41]
	v_lshl_add_u64 v[56:57], v[40:41], 0, v[64:65]
	v_lshl_add_u64 v[44:45], v[56:57], 1, s[40:41]
	ds_read_u16 v59, v120 offset:2448
	v_max_f32_e32 v55, v55, v55
	v_max_f32_e32 v55, 0, v55
	v_sqrt_f32_e32 v55, v55
	v_add_f32_e32 v46, 1.0, v46
	v_rcp_f32_e32 v46, v46
	s_waitcnt lgkmcnt(0)
	v_lshlrev_b32_e32 v59, 16, v59
	v_mul_f32_e32 v58, v58, v59
	v_mul_f32_e32 v55, v55, v58
	v_cvt_pk_bf16_f32 v58, v54, v55
	v_lshl_add_u64 v[54:55], v[56:57], 2, s[42:43]
	v_mul_f32_e32 v46, v46, v84
	global_store_dword v[54:55], v58, off
	v_add_f32_e32 v54, v46, v46
	v_cmp_ngt_f32_e32 vcc, s9, v54
	s_and_saveexec_b64 s[2:3], vcc
	s_xor_b64 s[2:3], exec, s[2:3]
	v_fmamk_f32 v55, v54, 0x3ab60b61, v169
	v_fmaak_f32 v55, v54, v55, 0x3d2aaaab
	v_fmaak_f32 v55, v54, v55, 0x3e2aaaab
	v_fma_f32 v55, v54, v55, 0.5
	v_fma_f32 v55, v54, v55, 1.0
	v_mul_f32_e64 v58, v55, -v54
	s_andn2_saveexec_b64 s[2:3], s[2:3]
	v_mul_f32_e32 v54, 0x3fb8aa3b, v54
	v_exp_f32_e32 v54, v54
	s_nop 0
	v_sub_f32_e32 v58, 1.0, v54
	s_or_b64 exec, exec, s[2:3]
	v_or_b32_e32 v54, 18, v66
	v_ashrrev_i32_e32 v55, 31, v54
	v_lshlrev_b64 v[54:55], 10, v[54:55]
	v_lshl_add_u64 v[60:61], v[54:55], 0, v[64:65]
	v_lshl_add_u64 v[56:57], v[60:61], 1, s[40:41]
	ds_read_u16 v59, v120 offset:2592
	v_add_f32_e32 v47, v47, v83
	v_mul_f32_e32 v47, 0xbfb8aa3b, v47
	v_add_f32_e32 v42, v42, v82
	v_exp_f32_e32 v47, v47
	v_mul_f32_e32 v42, 0xbfb8aa3b, v42
	v_exp_f32_e32 v42, v42
	v_max_f32_e32 v58, v58, v58
	v_add_f32_e32 v47, 1.0, v47
	v_rcp_f32_e32 v47, v47
	v_add_f32_e32 v42, 1.0, v42
	v_max_f32_e32 v58, 0, v58
	v_rcp_f32_e32 v63, v42
	v_sqrt_f32_e32 v62, v58
	v_mul_f32_e32 v58, v47, v84
	v_add_f32_e32 v42, v58, v58
	v_lshl_add_u64 v[60:61], v[60:61], 2, s[42:43]
	v_cmp_ngt_f32_e32 vcc, s9, v42
	s_waitcnt lgkmcnt(0)
;   __host__ __device__ __forceinline__ bf16_t* XC() const { return (bf16_t*)(wsl() + OFF_FFN); }
; __device__ __forceinline__ float bf2f(bf16_t h) { return __uint_as_float(((uint32_t)h) << 16); }
; __device__ __forceinline__ uint32_t pack2(float a, float b) { uint32_t r; asm("v_cvt_pk_bf16_f32 %0, %1, %2" : "=v"(r) : "v"(a), "v"(b)); return r; }
; __device__ __forceinline__ float sigmoidf_(float x) { return __builtin_amdgcn_rcpf(1.0f + __expf(-x)); }
; template <int EPI>
; __device__ __forceinline__ void gemm_tile(const Params& p, const EpiArgs& ea, const bf16_t* __restrict__ A, int lda,
;                                           const bf16_t* __restrict__ Bt, int K, int m0, int n0, char* smem) {
;     ...
;         for (int j = 0; j < 4; ++j) {
;           float r = sigmoidf_(acc[mi][nh * 2][j] + ba);
;           float ig = sigmoidf_(acc[mi][nh * 2 + 1][j] + bx);
;           float la = r * sp8;
;           float x2 = 2.0f * la;
;           float poly = -x2 * (1.0f + x2 * (0.5f + x2 * (0.16666667f + x2 * (0.041666668f + x2 * (0.008333334f + x2 * 0.0013888889f)))));
;           float em = (x2 < -0.3f) ? (1.0f - __expf(x2)) : poly;
;           float u = bf2f(p.XC()[(size_t)(r0 + j) * D + ch]);
;           float inp = __builtin_amdgcn_sqrtf(fmaxf(em, 0.0f)) * (ig * u);
;           ea.outu[(size_t)(r0 + j) * D + ch] = pack2(la, inp);
	v_lshlrev_b32_e32 v47, 16, v59
	v_mul_f32_e32 v47, v63, v47
	v_mul_f32_e32 v47, v62, v47
	v_cvt_pk_bf16_f32 v46, v46, v47
	global_store_dword v[60:61], v46, off
	s_and_saveexec_b64 s[2:3], vcc
	s_xor_b64 s[2:3], exec, s[2:3]
	v_fmamk_f32 v46, v42, 0x3ab60b61, v169
	v_fmaak_f32 v46, v42, v46, 0x3d2aaaab
	v_fmaak_f32 v46, v42, v46, 0x3e2aaaab
	v_fma_f32 v46, v42, v46, 0.5
	v_fma_f32 v46, v42, v46, 1.0
	v_mul_f32_e64 v59, v46, -v42
	s_andn2_saveexec_b64 s[2:3], s[2:3]
	v_mul_f32_e32 v42, 0x3fb8aa3b, v42
	v_exp_f32_e32 v42, v42
	s_nop 0
	v_sub_f32_e32 v59, 1.0, v42
	s_or_b64 exec, exec, s[2:3]
	v_add_f32_e32 v42, v43, v82
	v_mul_f32_e32 v42, 0xbfb8aa3b, v42
	v_exp_f32_e32 v42, v42
	v_add_f32_e32 v36, v36, v74
	v_mul_f32_e32 v36, 0xbfb8aa3b, v36
	v_exp_f32_e32 v36, v36
	v_add_f32_e32 v42, 1.0, v42
	v_rcp_f32_e32 v62, v42
	v_or_b32_e32 v42, 19, v66
	v_ashrrev_i32_e32 v43, 31, v42
	v_lshlrev_b64 v[42:43], 10, v[42:43]
	v_lshl_add_u64 v[60:61], v[42:43], 0, v[64:65]
	v_lshl_add_u64 v[46:47], v[60:61], 1, s[40:41]
	ds_read_u16 v63, v120 offset:2736
	v_max_f32_e32 v59, v59, v59
	v_max_f32_e32 v59, 0, v59
	v_sqrt_f32_e32 v59, v59
	v_add_f32_e32 v36, 1.0, v36
	v_rcp_f32_e32 v36, v36
	s_waitcnt lgkmcnt(0)
	v_lshlrev_b32_e32 v63, 16, v63
	v_mul_f32_e32 v62, v62, v63
	v_mul_f32_e32 v59, v59, v62
	v_cvt_pk_bf16_f32 v62, v58, v59
	v_lshl_add_u64 v[58:59], v[60:61], 2, s[42:43]
	v_mul_f32_e32 v36, v36, v72
	global_store_dword v[58:59], v62, off
	v_add_f32_e32 v58, v36, v36
	v_cmp_ngt_f32_e32 vcc, s9, v58
	s_and_saveexec_b64 s[2:3], vcc
	s_xor_b64 s[2:3], exec, s[2:3]
	v_fmamk_f32 v59, v58, 0x3ab60b61, v169
	v_fmaak_f32 v59, v58, v59, 0x3d2aaaab
	v_fmaak_f32 v59, v58, v59, 0x3e2aaaab
	v_fma_f32 v59, v58, v59, 0.5
	v_fma_f32 v59, v58, v59, 1.0
	v_mul_f32_e64 v59, v59, -v58
	s_andn2_saveexec_b64 s[2:3], s[2:3]
	v_mul_f32_e32 v58, 0x3fb8aa3b, v58
	v_exp_f32_e32 v58, v58
	s_nop 0
	v_sub_f32_e32 v59, 1.0, v58
	s_or_b64 exec, exec, s[2:3]
	ds_read_u16 v50, v120 offset:2336
	v_add_f32_e32 v37, v37, v74
	v_add_f32_e32 v32, v32, v67
	v_mul_f32_e32 v37, 0xbfb8aa3b, v37
	v_mul_f32_e32 v32, 0xbfb8aa3b, v32
	v_exp_f32_e32 v37, v37
	v_exp_f32_e32 v32, v32
	v_max_f32_e32 v51, v59, v59
	v_max_f32_e32 v51, 0, v51
	v_add_f32_e32 v37, 1.0, v37
	v_rcp_f32_e32 v37, v37
	v_add_f32_e32 v32, 1.0, v32
	v_rcp_f32_e32 v58, v32
	v_sqrt_f32_e32 v51, v51
	v_mul_f32_e32 v32, v37, v72
	v_lshl_add_u64 v[48:49], v[48:49], 0, v[52:53]
	v_add_f32_e32 v37, v32, v32
	v_lshl_add_u64 v[48:49], v[48:49], 2, s[42:43]
	v_cmp_ngt_f32_e32 vcc, s9, v37
	s_waitcnt lgkmcnt(0)
	v_lshlrev_b32_e32 v50, 16, v50
	v_mul_f32_e32 v50, v58, v50
	v_mul_f32_e32 v50, v51, v50
	v_cvt_pk_bf16_f32 v36, v36, v50
	global_store_dword v[48:49], v36, off
	s_and_saveexec_b64 s[2:3], vcc
	s_xor_b64 s[2:3], exec, s[2:3]
	v_fmamk_f32 v36, v37, 0x3ab60b61, v169
	v_fmaak_f32 v36, v37, v36, 0x3d2aaaab
	v_fmaak_f32 v36, v37, v36, 0x3e2aaaab
	v_fma_f32 v36, v37, v36, 0.5
	v_fma_f32 v36, v37, v36, 1.0
	v_mul_f32_e64 v36, v36, -v37
	s_andn2_saveexec_b64 s[2:3], s[2:3]
	v_mul_f32_e32 v36, 0x3fb8aa3b, v37
	v_exp_f32_e32 v36, v36
	s_nop 0
	v_sub_f32_e32 v36, 1.0, v36
	s_or_b64 exec, exec, s[2:3]
	ds_read_u16 v37, v120 offset:2480
	v_add_f32_e32 v38, v38, v74
	v_add_f32_e32 v33, v33, v67
	v_mul_f32_e32 v38, 0xbfb8aa3b, v38
	v_mul_f32_e32 v33, 0xbfb8aa3b, v33
	v_exp_f32_e32 v38, v38
	v_exp_f32_e32 v33, v33
	v_max_f32_e32 v36, v36, v36
	v_max_f32_e32 v36, 0, v36
	v_add_f32_e32 v38, 1.0, v38
	v_rcp_f32_e32 v38, v38
	v_add_f32_e32 v33, 1.0, v33
	v_rcp_f32_e32 v45, v33
	v_sqrt_f32_e32 v44, v36
	v_mul_f32_e32 v33, v38, v72
	v_lshl_add_u64 v[40:41], v[40:41], 0, v[52:53]
	v_add_f32_e32 v36, v33, v33
	v_lshl_add_u64 v[40:41], v[40:41], 2, s[42:43]
	v_cmp_ngt_f32_e32 vcc, s9, v36
	s_waitcnt lgkmcnt(0)
	v_lshlrev_b32_e32 v37, 16, v37
	v_mul_f32_e32 v37, v45, v37
	v_mul_f32_e32 v37, v44, v37
	v_cvt_pk_bf16_f32 v32, v32, v37
	global_store_dword v[40:41], v32, off
	s_and_saveexec_b64 s[2:3], vcc
	s_xor_b64 s[2:3], exec, s[2:3]
	v_fmamk_f32 v32, v36, 0x3ab60b61, v169
	v_fmaak_f32 v32, v36, v32, 0x3d2aaaab
	v_fmaak_f32 v32, v36, v32, 0x3e2aaaab
	v_fma_f32 v32, v36, v32, 0.5
	v_fma_f32 v32, v36, v32, 1.0
	v_mul_f32_e64 v32, v32, -v36
	s_andn2_saveexec_b64 s[2:3], s[2:3]
	v_mul_f32_e32 v32, 0x3fb8aa3b, v36
	v_exp_f32_e32 v32, v32
	s_nop 0
	v_sub_f32_e32 v32, 1.0, v32
	s_or_b64 exec, exec, s[2:3]
	ds_read_u16 v38, v120 offset:2624
	v_add_f32_e32 v39, v39, v74
	v_add_f32_e32 v34, v34, v67
	v_mul_f32_e32 v39, 0xbfb8aa3b, v39
	v_mul_f32_e32 v34, 0xbfb8aa3b, v34
	v_exp_f32_e32 v39, v39
	v_exp_f32_e32 v34, v34
	v_max_f32_e32 v32, v32, v32
	v_max_f32_e32 v32, 0, v32
	v_add_f32_e32 v39, 1.0, v39
	v_rcp_f32_e32 v39, v39
	v_sqrt_f32_e32 v40, v32
	v_add_f32_e32 v32, 1.0, v34
	v_rcp_f32_e32 v41, v32
	v_mul_f32_e32 v32, v39, v72
	v_lshl_add_u64 v[36:37], v[54:55], 0, v[52:53]
	v_add_f32_e32 v34, v32, v32
	v_lshl_add_u64 v[36:37], v[36:37], 2, s[42:43]
	v_cmp_ngt_f32_e32 vcc, s9, v34
	s_waitcnt lgkmcnt(0)
	v_lshlrev_b32_e32 v38, 16, v38
	v_mul_f32_e32 v38, v41, v38
	v_mul_f32_e32 v38, v40, v38
	v_cvt_pk_bf16_f32 v33, v33, v38
	global_store_dword v[36:37], v33, off
	s_and_saveexec_b64 s[2:3], vcc
	s_xor_b64 s[2:3], exec, s[2:3]
	v_fmamk_f32 v33, v34, 0x3ab60b61, v169
	v_fmaak_f32 v33, v34, v33, 0x3d2aaaab
	v_fmaak_f32 v33, v34, v33, 0x3e2aaaab
	v_fma_f32 v33, v34, v33, 0.5
	v_fma_f32 v33, v34, v33, 1.0
	v_mul_f32_e64 v33, v33, -v34
	s_andn2_saveexec_b64 s[2:3], s[2:3]
	v_mul_f32_e32 v33, 0x3fb8aa3b, v34
	v_exp_f32_e32 v33, v33
	s_nop 0
	v_sub_f32_e32 v33, 1.0, v33
	s_or_b64 exec, exec, s[2:3]
	ds_read_u16 v36, v120 offset:2768
	v_add_f32_e32 v28, v28, v83
	v_add_f32_e32 v37, v35, v67
	v_mul_f32_e32 v28, 0xbfb8aa3b, v28
	v_mul_f32_e32 v37, 0xbfb8aa3b, v37
	v_exp_f32_e32 v28, v28
	v_exp_f32_e32 v37, v37
	v_max_f32_e32 v33, v33, v33
	v_max_f32_e32 v33, 0, v33
	v_add_f32_e32 v28, 1.0, v28
	v_rcp_f32_e32 v28, v28
	v_sqrt_f32_e32 v38, v33
	v_add_f32_e32 v33, 1.0, v37
	v_rcp_f32_e32 v37, v33
	v_mul_f32_e32 v28, v28, v84
	v_lshl_add_u64 v[34:35], v[42:43], 0, v[52:53]
	v_add_f32_e32 v33, v28, v28
	v_lshl_add_u64 v[34:35], v[34:35], 2, s[42:43]
	v_cmp_ngt_f32_e32 vcc, s9, v33
	s_waitcnt lgkmcnt(0)
;   __host__ __device__ __forceinline__ bf16_t* XC() const { return (bf16_t*)(wsl() + OFF_FFN); }
; __device__ __forceinline__ float bf2f(bf16_t h) { return __uint_as_float(((uint32_t)h) << 16); }
; __device__ __forceinline__ uint32_t pack2(float a, float b) { uint32_t r; asm("v_cvt_pk_bf16_f32 %0, %1, %2" : "=v"(r) : "v"(a), "v"(b)); return r; }
; __device__ __forceinline__ float sigmoidf_(float x) { return __builtin_amdgcn_rcpf(1.0f + __expf(-x)); }
; template <int EPI>
; __device__ __forceinline__ void gemm_tile(const Params& p, const EpiArgs& ea, const bf16_t* __restrict__ A, int lda,
;                                           const bf16_t* __restrict__ Bt, int K, int m0, int n0, char* smem) {
;     ...
;         for (int j = 0; j < 4; ++j) {
;           float r = sigmoidf_(acc[mi][nh * 2][j] + ba);
;           float ig = sigmoidf_(acc[mi][nh * 2 + 1][j] + bx);
;           float la = r * sp8;
;           float x2 = 2.0f * la;
;           float poly = -x2 * (1.0f + x2 * (0.5f + x2 * (0.16666667f + x2 * (0.041666668f + x2 * (0.008333334f + x2 * 0.0013888889f)))));
;           float em = (x2 < -0.3f) ? (1.0f - __expf(x2)) : poly;
;           float u = bf2f(p.XC()[(size_t)(r0 + j) * D + ch]);
;           float inp = __builtin_amdgcn_sqrtf(fmaxf(em, 0.0f)) * (ig * u);
;           ea.outu[(size_t)(r0 + j) * D + ch] = pack2(la, inp);
	v_lshlrev_b32_e32 v36, 16, v36
	v_mul_f32_e32 v36, v37, v36
	v_mul_f32_e32 v36, v38, v36
	v_cvt_pk_bf16_f32 v32, v32, v36
	global_store_dword v[34:35], v32, off
	s_and_saveexec_b64 s[2:3], vcc
	s_xor_b64 s[2:3], exec, s[2:3]
	v_fmamk_f32 v32, v33, 0x3ab60b61, v169
	v_fmaak_f32 v32, v33, v32, 0x3d2aaaab
	v_fmaak_f32 v32, v33, v32, 0x3e2aaaab
	v_fma_f32 v32, v33, v32, 0.5
	v_fma_f32 v32, v33, v32, 1.0
	v_mul_f32_e64 v36, v32, -v33
	s_andn2_saveexec_b64 s[2:3], s[2:3]
	v_mul_f32_e32 v32, 0x3fb8aa3b, v33
	v_exp_f32_e32 v32, v32
	s_nop 0
	v_sub_f32_e32 v36, 1.0, v32
	s_or_b64 exec, exec, s[2:3]
	v_or_b32_e32 v32, 32, v66
	v_ashrrev_i32_e32 v33, 31, v32
	v_lshlrev_b64 v[32:33], 10, v[32:33]
	v_lshl_add_u64 v[38:39], v[32:33], 0, v[64:65]
	v_lshl_add_u64 v[34:35], v[38:39], 1, s[40:41]
	ds_read_u16 v37, v120 offset:4608
	v_add_f32_e32 v24, v24, v82
	v_mul_f32_e32 v24, 0xbfb8aa3b, v24
	v_exp_f32_e32 v24, v24
	v_max_f32_e32 v36, v36, v36
	v_max_f32_e32 v36, 0, v36
	v_sqrt_f32_e32 v36, v36
	v_add_f32_e32 v24, 1.0, v24
	v_rcp_f32_e32 v24, v24
	s_waitcnt lgkmcnt(0)
	v_lshlrev_b32_e32 v37, 16, v37
	v_mul_f32_e32 v24, v24, v37
	v_mul_f32_e32 v24, v36, v24
	v_cvt_pk_bf16_f32 v24, v28, v24
	v_lshl_add_u64 v[36:37], v[38:39], 2, s[42:43]
	global_store_dword v[36:37], v24, off
	v_add_f32_e32 v24, v29, v83
	v_mul_f32_e32 v24, 0xbfb8aa3b, v24
	v_exp_f32_e32 v24, v24
	s_nop 0
	v_add_f32_e32 v24, 1.0, v24
	v_rcp_f32_e32 v24, v24
	s_nop 0
	v_mul_f32_e32 v36, v24, v84
	v_add_f32_e32 v24, v36, v36
	v_cmp_ngt_f32_e32 vcc, s9, v24
	s_and_saveexec_b64 s[2:3], vcc
	s_xor_b64 s[2:3], exec, s[2:3]
	v_fmamk_f32 v28, v24, 0x3ab60b61, v169
	v_fmaak_f32 v28, v24, v28, 0x3d2aaaab
	v_fmaak_f32 v28, v24, v28, 0x3e2aaaab
	v_fma_f32 v28, v24, v28, 0.5
	v_fma_f32 v28, v24, v28, 1.0
	v_mul_f32_e64 v37, v28, -v24
	s_andn2_saveexec_b64 s[2:3], s[2:3]
	v_mul_f32_e32 v24, 0x3fb8aa3b, v24
	v_exp_f32_e32 v24, v24
	s_nop 0
	v_sub_f32_e32 v37, 1.0, v24
	s_or_b64 exec, exec, s[2:3]
	v_add_f32_e32 v24, v25, v82
	v_mul_f32_e32 v24, 0xbfb8aa3b, v24
	v_exp_f32_e32 v24, v24
	v_add_f32_e32 v30, v30, v83
	v_mul_f32_e32 v30, 0xbfb8aa3b, v30
	v_exp_f32_e32 v30, v30
	v_add_f32_e32 v24, 1.0, v24
	v_rcp_f32_e32 v40, v24
	v_or_b32_e32 v24, 33, v66
	v_ashrrev_i32_e32 v25, 31, v24
	v_lshlrev_b64 v[24:25], 10, v[24:25]
	v_lshl_add_u64 v[38:39], v[24:25], 0, v[64:65]
	v_lshl_add_u64 v[28:29], v[38:39], 1, s[40:41]
	ds_read_u16 v41, v120 offset:4752
	v_max_f32_e32 v37, v37, v37
	v_max_f32_e32 v37, 0, v37
	v_sqrt_f32_e32 v37, v37
	v_add_f32_e32 v30, 1.0, v30
	v_rcp_f32_e32 v30, v30
	s_waitcnt lgkmcnt(0)
	v_lshlrev_b32_e32 v41, 16, v41
	v_mul_f32_e32 v40, v40, v41
	v_mul_f32_e32 v37, v37, v40
	v_cvt_pk_bf16_f32 v40, v36, v37
	v_lshl_add_u64 v[36:37], v[38:39], 2, s[42:43]
	v_mul_f32_e32 v30, v30, v84
	global_store_dword v[36:37], v40, off
	v_add_f32_e32 v36, v30, v30
	v_cmp_ngt_f32_e32 vcc, s9, v36
	s_and_saveexec_b64 s[2:3], vcc
	s_xor_b64 s[2:3], exec, s[2:3]
	v_fmamk_f32 v37, v36, 0x3ab60b61, v169
	v_fmaak_f32 v37, v36, v37, 0x3d2aaaab
	v_fmaak_f32 v37, v36, v37, 0x3e2aaaab
	v_fma_f32 v37, v36, v37, 0.5
	v_fma_f32 v37, v36, v37, 1.0
	v_mul_f32_e64 v40, v37, -v36
	s_andn2_saveexec_b64 s[2:3], s[2:3]
	v_mul_f32_e32 v36, 0x3fb8aa3b, v36
	v_exp_f32_e32 v36, v36
	s_nop 0
	v_sub_f32_e32 v40, 1.0, v36
	s_or_b64 exec, exec, s[2:3]
	v_or_b32_e32 v36, 34, v66
	v_ashrrev_i32_e32 v37, 31, v36
	v_lshlrev_b64 v[36:37], 10, v[36:37]
	v_lshl_add_u64 v[42:43], v[36:37], 0, v[64:65]
	v_lshl_add_u64 v[38:39], v[42:43], 1, s[40:41]
	ds_read_u16 v41, v120 offset:4896
	v_add_f32_e32 v31, v31, v83
	v_mul_f32_e32 v31, 0xbfb8aa3b, v31
	v_add_f32_e32 v26, v26, v82
	v_exp_f32_e32 v31, v31
	v_mul_f32_e32 v26, 0xbfb8aa3b, v26
	v_exp_f32_e32 v26, v26
	v_max_f32_e32 v40, v40, v40
	v_add_f32_e32 v31, 1.0, v31
	v_rcp_f32_e32 v31, v31
	v_add_f32_e32 v26, 1.0, v26
	v_max_f32_e32 v40, 0, v40
	v_rcp_f32_e32 v45, v26
	v_sqrt_f32_e32 v44, v40
	v_mul_f32_e32 v40, v31, v84
	v_add_f32_e32 v26, v40, v40
	v_lshl_add_u64 v[42:43], v[42:43], 2, s[42:43]
	v_cmp_ngt_f32_e32 vcc, s9, v26
	s_waitcnt lgkmcnt(0)
	v_lshlrev_b32_e32 v31, 16, v41
	v_mul_f32_e32 v31, v45, v31
	v_mul_f32_e32 v31, v44, v31
	v_cvt_pk_bf16_f32 v30, v30, v31
	global_store_dword v[42:43], v30, off
	s_and_saveexec_b64 s[2:3], vcc
	s_xor_b64 s[2:3], exec, s[2:3]
	v_fmamk_f32 v30, v26, 0x3ab60b61, v169
	v_fmaak_f32 v30, v26, v30, 0x3d2aaaab
	v_fmaak_f32 v30, v26, v30, 0x3e2aaaab
	v_fma_f32 v30, v26, v30, 0.5
	v_fma_f32 v30, v26, v30, 1.0
	v_mul_f32_e64 v41, v30, -v26
	s_andn2_saveexec_b64 s[2:3], s[2:3]
	v_mul_f32_e32 v26, 0x3fb8aa3b, v26
	v_exp_f32_e32 v26, v26
	s_nop 0
	v_sub_f32_e32 v41, 1.0, v26
	s_or_b64 exec, exec, s[2:3]
	v_add_f32_e32 v26, v27, v82
	v_mul_f32_e32 v26, 0xbfb8aa3b, v26
	v_exp_f32_e32 v26, v26
	v_add_f32_e32 v20, v20, v74
	v_mul_f32_e32 v20, 0xbfb8aa3b, v20
	v_exp_f32_e32 v20, v20
	v_add_f32_e32 v26, 1.0, v26
	v_rcp_f32_e32 v44, v26
	v_or_b32_e32 v26, 35, v66
	v_ashrrev_i32_e32 v27, 31, v26
	v_lshlrev_b64 v[26:27], 10, v[26:27]
	v_lshl_add_u64 v[42:43], v[26:27], 0, v[64:65]
	v_lshl_add_u64 v[30:31], v[42:43], 1, s[40:41]
	ds_read_u16 v45, v120 offset:5040
	v_max_f32_e32 v41, v41, v41
	v_max_f32_e32 v41, 0, v41
	v_sqrt_f32_e32 v41, v41
	v_add_f32_e32 v20, 1.0, v20
	v_rcp_f32_e32 v20, v20
	s_waitcnt lgkmcnt(0)
;   __host__ __device__ __forceinline__ bf16_t* XC() const { return (bf16_t*)(wsl() + OFF_FFN); }
; __device__ __forceinline__ float bf2f(bf16_t h) { return __uint_as_float(((uint32_t)h) << 16); }
; __device__ __forceinline__ uint32_t pack2(float a, float b) { uint32_t r; asm("v_cvt_pk_bf16_f32 %0, %1, %2" : "=v"(r) : "v"(a), "v"(b)); return r; }
; __device__ __forceinline__ float sigmoidf_(float x) { return __builtin_amdgcn_rcpf(1.0f + __expf(-x)); }
; template <int EPI>
; __device__ __forceinline__ void gemm_tile(const Params& p, const EpiArgs& ea, const bf16_t* __restrict__ A, int lda,
;                                           const bf16_t* __restrict__ Bt, int K, int m0, int n0, char* smem) {
;     ...
;         for (int j = 0; j < 4; ++j) {
;           float r = sigmoidf_(acc[mi][nh * 2][j] + ba);
;           float ig = sigmoidf_(acc[mi][nh * 2 + 1][j] + bx);
;           float la = r * sp8;
;           float x2 = 2.0f * la;
;           float poly = -x2 * (1.0f + x2 * (0.5f + x2 * (0.16666667f + x2 * (0.041666668f + x2 * (0.008333334f + x2 * 0.0013888889f)))));
;           float em = (x2 < -0.3f) ? (1.0f - __expf(x2)) : poly;
;           float u = bf2f(p.XC()[(size_t)(r0 + j) * D + ch]);
;           float inp = __builtin_amdgcn_sqrtf(fmaxf(em, 0.0f)) * (ig * u);
;           ea.outu[(size_t)(r0 + j) * D + ch] = pack2(la, inp);
	v_lshlrev_b32_e32 v45, 16, v45
	v_mul_f32_e32 v44, v44, v45
	v_mul_f32_e32 v41, v41, v44
	v_cvt_pk_bf16_f32 v44, v40, v41
	v_lshl_add_u64 v[40:41], v[42:43], 2, s[42:43]
	v_mul_f32_e32 v20, v20, v72
	global_store_dword v[40:41], v44, off
	v_add_f32_e32 v40, v20, v20
	v_cmp_ngt_f32_e32 vcc, s9, v40
	s_and_saveexec_b64 s[2:3], vcc
	s_xor_b64 s[2:3], exec, s[2:3]
	v_fmamk_f32 v41, v40, 0x3ab60b61, v169
	v_fmaak_f32 v41, v40, v41, 0x3d2aaaab
	v_fmaak_f32 v41, v40, v41, 0x3e2aaaab
	v_fma_f32 v41, v40, v41, 0.5
	v_fma_f32 v41, v40, v41, 1.0
	v_mul_f32_e64 v41, v41, -v40
	s_andn2_saveexec_b64 s[2:3], s[2:3]
	v_mul_f32_e32 v40, 0x3fb8aa3b, v40
	v_exp_f32_e32 v40, v40
	s_nop 0
	v_sub_f32_e32 v41, 1.0, v40
	s_or_b64 exec, exec, s[2:3]
	ds_read_u16 v34, v120 offset:4640
	v_add_f32_e32 v21, v21, v74
	v_add_f32_e32 v16, v16, v67
	v_mul_f32_e32 v21, 0xbfb8aa3b, v21
	v_mul_f32_e32 v16, 0xbfb8aa3b, v16
	v_exp_f32_e32 v21, v21
	v_exp_f32_e32 v16, v16
	v_max_f32_e32 v35, v41, v41
	v_max_f32_e32 v35, 0, v35
	v_add_f32_e32 v21, 1.0, v21
	v_rcp_f32_e32 v21, v21
	v_add_f32_e32 v16, 1.0, v16
	v_rcp_f32_e32 v40, v16
	v_sqrt_f32_e32 v35, v35
	v_mul_f32_e32 v16, v21, v72
	v_lshl_add_u64 v[32:33], v[32:33], 0, v[52:53]
	v_add_f32_e32 v21, v16, v16
	v_lshl_add_u64 v[32:33], v[32:33], 2, s[42:43]
	v_cmp_ngt_f32_e32 vcc, s9, v21
	s_waitcnt lgkmcnt(0)
	v_lshlrev_b32_e32 v34, 16, v34
	v_mul_f32_e32 v34, v40, v34
	v_mul_f32_e32 v34, v35, v34
	v_cvt_pk_bf16_f32 v20, v20, v34
	global_store_dword v[32:33], v20, off
	s_and_saveexec_b64 s[2:3], vcc
	s_xor_b64 s[2:3], exec, s[2:3]
	v_fmamk_f32 v20, v21, 0x3ab60b61, v169
	v_fmaak_f32 v20, v21, v20, 0x3d2aaaab
	v_fmaak_f32 v20, v21, v20, 0x3e2aaaab
	v_fma_f32 v20, v21, v20, 0.5
	v_fma_f32 v20, v21, v20, 1.0
	v_mul_f32_e64 v20, v20, -v21
	s_andn2_saveexec_b64 s[2:3], s[2:3]
	v_mul_f32_e32 v20, 0x3fb8aa3b, v21
	v_exp_f32_e32 v20, v20
	s_nop 0
	v_sub_f32_e32 v20, 1.0, v20
	s_or_b64 exec, exec, s[2:3]
	ds_read_u16 v21, v120 offset:4784
	v_add_f32_e32 v22, v22, v74
	v_add_f32_e32 v17, v17, v67
	v_mul_f32_e32 v22, 0xbfb8aa3b, v22
	v_mul_f32_e32 v17, 0xbfb8aa3b, v17
	v_exp_f32_e32 v22, v22
	v_exp_f32_e32 v17, v17
	v_max_f32_e32 v20, v20, v20
	v_max_f32_e32 v20, 0, v20
	v_add_f32_e32 v22, 1.0, v22
	v_rcp_f32_e32 v22, v22
	v_add_f32_e32 v17, 1.0, v17
	v_rcp_f32_e32 v29, v17
	v_sqrt_f32_e32 v28, v20
	v_mul_f32_e32 v17, v22, v72
	v_lshl_add_u64 v[24:25], v[24:25], 0, v[52:53]
	v_add_f32_e32 v20, v17, v17
	v_lshl_add_u64 v[24:25], v[24:25], 2, s[42:43]
	v_cmp_ngt_f32_e32 vcc, s9, v20
	s_waitcnt lgkmcnt(0)
	v_lshlrev_b32_e32 v21, 16, v21
	v_mul_f32_e32 v21, v29, v21
	v_mul_f32_e32 v21, v28, v21
	v_cvt_pk_bf16_f32 v16, v16, v21
	global_store_dword v[24:25], v16, off
	s_and_saveexec_b64 s[2:3], vcc
	s_xor_b64 s[2:3], exec, s[2:3]
	v_fmamk_f32 v16, v20, 0x3ab60b61, v169
	v_fmaak_f32 v16, v20, v16, 0x3d2aaaab
	v_fmaak_f32 v16, v20, v16, 0x3e2aaaab
	v_fma_f32 v16, v20, v16, 0.5
	v_fma_f32 v16, v20, v16, 1.0
	v_mul_f32_e64 v16, v16, -v20
	s_andn2_saveexec_b64 s[2:3], s[2:3]
	v_mul_f32_e32 v16, 0x3fb8aa3b, v20
	v_exp_f32_e32 v16, v16
	s_nop 0
	v_sub_f32_e32 v16, 1.0, v16
	s_or_b64 exec, exec, s[2:3]
	ds_read_u16 v22, v120 offset:4928
	v_add_f32_e32 v23, v23, v74
	v_add_f32_e32 v18, v18, v67
	v_mul_f32_e32 v23, 0xbfb8aa3b, v23
	v_mul_f32_e32 v18, 0xbfb8aa3b, v18
	v_exp_f32_e32 v23, v23
	v_exp_f32_e32 v18, v18
	v_max_f32_e32 v16, v16, v16
	v_max_f32_e32 v16, 0, v16
	v_add_f32_e32 v23, 1.0, v23
	v_rcp_f32_e32 v23, v23
	v_sqrt_f32_e32 v24, v16
	v_add_f32_e32 v16, 1.0, v18
	v_rcp_f32_e32 v25, v16
	v_mul_f32_e32 v16, v23, v72
	v_lshl_add_u64 v[20:21], v[36:37], 0, v[52:53]
	v_add_f32_e32 v18, v16, v16
	v_lshl_add_u64 v[20:21], v[20:21], 2, s[42:43]
	v_cmp_ngt_f32_e32 vcc, s9, v18
	s_waitcnt lgkmcnt(0)
	v_lshlrev_b32_e32 v22, 16, v22
	v_mul_f32_e32 v22, v25, v22
	v_mul_f32_e32 v22, v24, v22
	v_cvt_pk_bf16_f32 v17, v17, v22
	global_store_dword v[20:21], v17, off
	s_and_saveexec_b64 s[2:3], vcc
	s_xor_b64 s[2:3], exec, s[2:3]
	v_fmamk_f32 v17, v18, 0x3ab60b61, v169
	v_fmaak_f32 v17, v18, v17, 0x3d2aaaab
	v_fmaak_f32 v17, v18, v17, 0x3e2aaaab
	v_fma_f32 v17, v18, v17, 0.5
	v_fma_f32 v17, v18, v17, 1.0
	v_mul_f32_e64 v17, v17, -v18
	s_andn2_saveexec_b64 s[2:3], s[2:3]
	v_mul_f32_e32 v17, 0x3fb8aa3b, v18
	v_exp_f32_e32 v17, v17
	s_nop 0
	v_sub_f32_e32 v17, 1.0, v17
	s_or_b64 exec, exec, s[2:3]
	ds_read_u16 v20, v120 offset:5072
	v_add_f32_e32 v12, v12, v83
	v_add_f32_e32 v21, v19, v67
	v_mul_f32_e32 v12, 0xbfb8aa3b, v12
	v_mul_f32_e32 v21, 0xbfb8aa3b, v21
	v_exp_f32_e32 v12, v12
	v_exp_f32_e32 v21, v21
	v_max_f32_e32 v17, v17, v17
	v_max_f32_e32 v17, 0, v17
	v_add_f32_e32 v12, 1.0, v12
	v_rcp_f32_e32 v12, v12
	v_sqrt_f32_e32 v22, v17
	v_add_f32_e32 v17, 1.0, v21
	v_rcp_f32_e32 v21, v17
	v_mul_f32_e32 v12, v12, v84
	v_lshl_add_u64 v[18:19], v[26:27], 0, v[52:53]
	v_add_f32_e32 v17, v12, v12
	v_lshl_add_u64 v[18:19], v[18:19], 2, s[42:43]
	v_cmp_ngt_f32_e32 vcc, s9, v17
	s_waitcnt lgkmcnt(0)
	v_lshlrev_b32_e32 v20, 16, v20
	v_mul_f32_e32 v20, v21, v20
	v_mul_f32_e32 v20, v22, v20
	v_cvt_pk_bf16_f32 v16, v16, v20
	global_store_dword v[18:19], v16, off
	s_and_saveexec_b64 s[2:3], vcc
	s_xor_b64 s[2:3], exec, s[2:3]
	v_fmamk_f32 v16, v17, 0x3ab60b61, v169
	v_fmaak_f32 v16, v17, v16, 0x3d2aaaab
	v_fmaak_f32 v16, v17, v16, 0x3e2aaaab
	v_fma_f32 v16, v17, v16, 0.5
	v_fma_f32 v16, v17, v16, 1.0
	v_mul_f32_e64 v20, v16, -v17
	s_andn2_saveexec_b64 s[2:3], s[2:3]
	v_mul_f32_e32 v16, 0x3fb8aa3b, v17
	v_exp_f32_e32 v16, v16
	s_nop 0
	v_sub_f32_e32 v20, 1.0, v16
	s_or_b64 exec, exec, s[2:3]
	v_or_b32_e32 v16, 48, v66
	v_ashrrev_i32_e32 v17, 31, v16
	v_lshlrev_b64 v[16:17], 10, v[16:17]
	v_lshl_add_u64 v[22:23], v[16:17], 0, v[64:65]
	v_lshl_add_u64 v[18:19], v[22:23], 1, s[40:41]
	ds_read_u16 v21, v120 offset:6912
	v_add_f32_e32 v8, v8, v82
	v_mul_f32_e32 v8, 0xbfb8aa3b, v8
	v_exp_f32_e32 v8, v8
	v_max_f32_e32 v20, v20, v20
	v_max_f32_e32 v20, 0, v20
	v_sqrt_f32_e32 v20, v20
	v_add_f32_e32 v8, 1.0, v8
	v_rcp_f32_e32 v8, v8
	s_waitcnt lgkmcnt(0)
;   __host__ __device__ __forceinline__ bf16_t* XC() const { return (bf16_t*)(wsl() + OFF_FFN); }
; __device__ __forceinline__ float bf2f(bf16_t h) { return __uint_as_float(((uint32_t)h) << 16); }
; __device__ __forceinline__ uint32_t pack2(float a, float b) { uint32_t r; asm("v_cvt_pk_bf16_f32 %0, %1, %2" : "=v"(r) : "v"(a), "v"(b)); return r; }
; __device__ __forceinline__ float sigmoidf_(float x) { return __builtin_amdgcn_rcpf(1.0f + __expf(-x)); }
; template <int EPI>
; __device__ __forceinline__ void gemm_tile(const Params& p, const EpiArgs& ea, const bf16_t* __restrict__ A, int lda,
;                                           const bf16_t* __restrict__ Bt, int K, int m0, int n0, char* smem) {
;     ...
;         for (int j = 0; j < 4; ++j) {
;           float r = sigmoidf_(acc[mi][nh * 2][j] + ba);
;           float ig = sigmoidf_(acc[mi][nh * 2 + 1][j] + bx);
;           float la = r * sp8;
;           float x2 = 2.0f * la;
;           float poly = -x2 * (1.0f + x2 * (0.5f + x2 * (0.16666667f + x2 * (0.041666668f + x2 * (0.008333334f + x2 * 0.0013888889f)))));
;           float em = (x2 < -0.3f) ? (1.0f - __expf(x2)) : poly;
;           float u = bf2f(p.XC()[(size_t)(r0 + j) * D + ch]);
;           float inp = __builtin_amdgcn_sqrtf(fmaxf(em, 0.0f)) * (ig * u);
;           ea.outu[(size_t)(r0 + j) * D + ch] = pack2(la, inp);
	v_lshlrev_b32_e32 v21, 16, v21
	v_mul_f32_e32 v8, v8, v21
	v_mul_f32_e32 v8, v20, v8
	v_cvt_pk_bf16_f32 v8, v12, v8
	v_lshl_add_u64 v[20:21], v[22:23], 2, s[42:43]
	global_store_dword v[20:21], v8, off
	v_add_f32_e32 v8, v13, v83
	v_mul_f32_e32 v8, 0xbfb8aa3b, v8
	v_exp_f32_e32 v8, v8
	s_nop 0
	v_add_f32_e32 v8, 1.0, v8
	v_rcp_f32_e32 v8, v8
	s_nop 0
	v_mul_f32_e32 v20, v8, v84
	v_add_f32_e32 v8, v20, v20
	v_cmp_ngt_f32_e32 vcc, s9, v8
	s_and_saveexec_b64 s[2:3], vcc
	s_xor_b64 s[2:3], exec, s[2:3]
	v_fmamk_f32 v12, v8, 0x3ab60b61, v169
	v_fmaak_f32 v12, v8, v12, 0x3d2aaaab
	v_fmaak_f32 v12, v8, v12, 0x3e2aaaab
	v_fma_f32 v12, v8, v12, 0.5
	v_fma_f32 v12, v8, v12, 1.0
	v_mul_f32_e64 v21, v12, -v8
	s_andn2_saveexec_b64 s[2:3], s[2:3]
	v_mul_f32_e32 v8, 0x3fb8aa3b, v8
	v_exp_f32_e32 v8, v8
	s_nop 0
	v_sub_f32_e32 v21, 1.0, v8
	s_or_b64 exec, exec, s[2:3]
	v_add_f32_e32 v8, v9, v82
	v_mul_f32_e32 v8, 0xbfb8aa3b, v8
	v_exp_f32_e32 v8, v8
	v_add_f32_e32 v14, v14, v83
	v_mul_f32_e32 v14, 0xbfb8aa3b, v14
	v_exp_f32_e32 v14, v14
	v_add_f32_e32 v8, 1.0, v8
	v_rcp_f32_e32 v24, v8
	v_or_b32_e32 v8, 49, v66
	v_ashrrev_i32_e32 v9, 31, v8
	v_lshlrev_b64 v[8:9], 10, v[8:9]
	v_lshl_add_u64 v[22:23], v[8:9], 0, v[64:65]
	v_lshl_add_u64 v[12:13], v[22:23], 1, s[40:41]
	ds_read_u16 v25, v120 offset:7056
	v_max_f32_e32 v21, v21, v21
	v_max_f32_e32 v21, 0, v21
	v_sqrt_f32_e32 v21, v21
	v_add_f32_e32 v14, 1.0, v14
	v_rcp_f32_e32 v14, v14
	s_waitcnt lgkmcnt(0)
	v_lshlrev_b32_e32 v25, 16, v25
	v_mul_f32_e32 v24, v24, v25
	v_mul_f32_e32 v21, v21, v24
	v_cvt_pk_bf16_f32 v24, v20, v21
	v_lshl_add_u64 v[20:21], v[22:23], 2, s[42:43]
	v_mul_f32_e32 v14, v14, v84
	global_store_dword v[20:21], v24, off
	v_add_f32_e32 v20, v14, v14
	v_cmp_ngt_f32_e32 vcc, s9, v20
	s_and_saveexec_b64 s[2:3], vcc
	s_xor_b64 s[2:3], exec, s[2:3]
	v_fmamk_f32 v21, v20, 0x3ab60b61, v169
	v_fmaak_f32 v21, v20, v21, 0x3d2aaaab
	v_fmaak_f32 v21, v20, v21, 0x3e2aaaab
	v_fma_f32 v21, v20, v21, 0.5
	v_fma_f32 v21, v20, v21, 1.0
	v_mul_f32_e64 v24, v21, -v20
	s_andn2_saveexec_b64 s[2:3], s[2:3]
	v_mul_f32_e32 v20, 0x3fb8aa3b, v20
	v_exp_f32_e32 v20, v20
	s_nop 0
	v_sub_f32_e32 v24, 1.0, v20
	s_or_b64 exec, exec, s[2:3]
	v_or_b32_e32 v20, 50, v66
	v_ashrrev_i32_e32 v21, 31, v20
	v_lshlrev_b64 v[20:21], 10, v[20:21]
	v_lshl_add_u64 v[26:27], v[20:21], 0, v[64:65]
	v_lshl_add_u64 v[22:23], v[26:27], 1, s[40:41]
	ds_read_u16 v25, v120 offset:7200
	v_add_f32_e32 v15, v15, v83
	v_mul_f32_e32 v15, 0xbfb8aa3b, v15
	v_add_f32_e32 v10, v10, v82
	v_exp_f32_e32 v15, v15
	v_mul_f32_e32 v10, 0xbfb8aa3b, v10
	v_exp_f32_e32 v10, v10
	v_max_f32_e32 v24, v24, v24
	v_add_f32_e32 v15, 1.0, v15
	v_rcp_f32_e32 v15, v15
	v_add_f32_e32 v10, 1.0, v10
	v_max_f32_e32 v24, 0, v24
	v_rcp_f32_e32 v29, v10
	v_sqrt_f32_e32 v28, v24
	v_mul_f32_e32 v24, v15, v84
	v_add_f32_e32 v10, v24, v24
	v_lshl_add_u64 v[26:27], v[26:27], 2, s[42:43]
	v_cmp_ngt_f32_e32 vcc, s9, v10
	s_waitcnt lgkmcnt(0)
	v_lshlrev_b32_e32 v15, 16, v25
	v_mul_f32_e32 v15, v29, v15
	v_mul_f32_e32 v15, v28, v15
	v_cvt_pk_bf16_f32 v14, v14, v15
	global_store_dword v[26:27], v14, off
	s_and_saveexec_b64 s[2:3], vcc
	s_xor_b64 s[2:3], exec, s[2:3]
	v_fmamk_f32 v14, v10, 0x3ab60b61, v169
	v_fmaak_f32 v14, v10, v14, 0x3d2aaaab
	v_fmaak_f32 v14, v10, v14, 0x3e2aaaab
	v_fma_f32 v14, v10, v14, 0.5
	v_fma_f32 v14, v10, v14, 1.0
	v_mul_f32_e64 v25, v14, -v10
	s_andn2_saveexec_b64 s[2:3], s[2:3]
	v_mul_f32_e32 v10, 0x3fb8aa3b, v10
	v_exp_f32_e32 v10, v10
	s_nop 0
	v_sub_f32_e32 v25, 1.0, v10
	s_or_b64 exec, exec, s[2:3]
	v_add_f32_e32 v10, v11, v82
	v_mul_f32_e32 v10, 0xbfb8aa3b, v10
	v_exp_f32_e32 v10, v10
	v_add_f32_e32 v4, v4, v74
	v_mul_f32_e32 v4, 0xbfb8aa3b, v4
	v_exp_f32_e32 v4, v4
	v_add_f32_e32 v10, 1.0, v10
	v_rcp_f32_e32 v28, v10
	v_or_b32_e32 v10, 51, v66
	v_ashrrev_i32_e32 v11, 31, v10
	v_lshlrev_b64 v[10:11], 10, v[10:11]
	v_lshl_add_u64 v[26:27], v[10:11], 0, v[64:65]
	v_lshl_add_u64 v[14:15], v[26:27], 1, s[40:41]
	ds_read_u16 v29, v120 offset:7344
	v_max_f32_e32 v25, v25, v25
	v_max_f32_e32 v25, 0, v25
	v_sqrt_f32_e32 v25, v25
	v_add_f32_e32 v4, 1.0, v4
	v_rcp_f32_e32 v4, v4
	s_waitcnt lgkmcnt(0)
;   __host__ __device__ __forceinline__ bf16_t* XC() const { return (bf16_t*)(wsl() + OFF_FFN); }
; __device__ __forceinline__ float bf2f(bf16_t h) { return __uint_as_float(((uint32_t)h) << 16); }
; __device__ __forceinline__ uint32_t pack2(float a, float b) { uint32_t r; asm("v_cvt_pk_bf16_f32 %0, %1, %2" : "=v"(r) : "v"(a), "v"(b)); return r; }
; __device__ __forceinline__ float sigmoidf_(float x) { return __builtin_amdgcn_rcpf(1.0f + __expf(-x)); }
; template <int EPI>
; __device__ __forceinline__ void gemm_tile(const Params& p, const EpiArgs& ea, const bf16_t* __restrict__ A, int lda,
;                                           const bf16_t* __restrict__ Bt, int K, int m0, int n0, char* smem) {
;     ...
;     __syncthreads();
;     ...
;         for (int j = 0; j < 4; ++j) {
;           float r = sigmoidf_(acc[mi][nh * 2][j] + ba);
;           float ig = sigmoidf_(acc[mi][nh * 2 + 1][j] + bx);
;           float la = r * sp8;
;           float x2 = 2.0f * la;
;           float poly = -x2 * (1.0f + x2 * (0.5f + x2 * (0.16666667f + x2 * (0.041666668f + x2 * (0.008333334f + x2 * 0.0013888889f)))));
;           float em = (x2 < -0.3f) ? (1.0f - __expf(x2)) : poly;
;           float u = bf2f(p.XC()[(size_t)(r0 + j) * D + ch]);
;           float inp = __builtin_amdgcn_sqrtf(fmaxf(em, 0.0f)) * (ig * u);
;           ea.outu[(size_t)(r0 + j) * D + ch] = pack2(la, inp);
;         }
;       }
;     }
;   }
; }
	v_lshlrev_b32_e32 v29, 16, v29
	v_mul_f32_e32 v28, v28, v29
	v_mul_f32_e32 v25, v25, v28
	v_cvt_pk_bf16_f32 v28, v24, v25
	v_lshl_add_u64 v[24:25], v[26:27], 2, s[42:43]
	v_mul_f32_e32 v4, v4, v72
	global_store_dword v[24:25], v28, off
	v_add_f32_e32 v24, v4, v4
	v_cmp_ngt_f32_e32 vcc, s9, v24
	s_and_saveexec_b64 s[2:3], vcc
	s_xor_b64 s[2:3], exec, s[2:3]
	v_fmamk_f32 v25, v24, 0x3ab60b61, v169
	v_fmaak_f32 v25, v24, v25, 0x3d2aaaab
	v_fmaak_f32 v25, v24, v25, 0x3e2aaaab
	v_fma_f32 v25, v24, v25, 0.5
	v_fma_f32 v25, v24, v25, 1.0
	v_mul_f32_e64 v25, v25, -v24
	s_andn2_saveexec_b64 s[2:3], s[2:3]
	v_mul_f32_e32 v24, 0x3fb8aa3b, v24
	v_exp_f32_e32 v24, v24
	s_nop 0
	v_sub_f32_e32 v25, 1.0, v24
	s_or_b64 exec, exec, s[2:3]
	ds_read_u16 v18, v120 offset:6944
	v_add_f32_e32 v5, v5, v74
	v_add_f32_e32 v0, v0, v67
	v_mul_f32_e32 v5, 0xbfb8aa3b, v5
	v_mul_f32_e32 v0, 0xbfb8aa3b, v0
	v_exp_f32_e32 v5, v5
	v_exp_f32_e32 v0, v0
	v_max_f32_e32 v19, v25, v25
	v_max_f32_e32 v19, 0, v19
	v_add_f32_e32 v5, 1.0, v5
	v_rcp_f32_e32 v5, v5
	v_add_f32_e32 v0, 1.0, v0
	v_rcp_f32_e32 v24, v0
	v_sqrt_f32_e32 v19, v19
	v_mul_f32_e32 v0, v5, v72
	v_lshl_add_u64 v[16:17], v[16:17], 0, v[52:53]
	v_add_f32_e32 v5, v0, v0
	v_lshl_add_u64 v[16:17], v[16:17], 2, s[42:43]
	v_cmp_ngt_f32_e32 vcc, s9, v5
	s_waitcnt lgkmcnt(0)
	v_lshlrev_b32_e32 v18, 16, v18
	v_mul_f32_e32 v18, v24, v18
	v_mul_f32_e32 v18, v19, v18
	v_cvt_pk_bf16_f32 v4, v4, v18
	global_store_dword v[16:17], v4, off
	s_and_saveexec_b64 s[2:3], vcc
	s_xor_b64 s[2:3], exec, s[2:3]
	v_fmamk_f32 v4, v5, 0x3ab60b61, v169
	v_fmaak_f32 v4, v5, v4, 0x3d2aaaab
	v_fmaak_f32 v4, v5, v4, 0x3e2aaaab
	v_fma_f32 v4, v5, v4, 0.5
	v_fma_f32 v4, v5, v4, 1.0
	v_mul_f32_e64 v4, v4, -v5
	s_andn2_saveexec_b64 s[2:3], s[2:3]
	v_mul_f32_e32 v4, 0x3fb8aa3b, v5
	v_exp_f32_e32 v4, v4
	s_nop 0
	v_sub_f32_e32 v4, 1.0, v4
	s_or_b64 exec, exec, s[2:3]
	ds_read_u16 v5, v120 offset:7088
	v_add_f32_e32 v6, v6, v74
	v_add_f32_e32 v1, v1, v67
	v_mul_f32_e32 v6, 0xbfb8aa3b, v6
	v_mul_f32_e32 v1, 0xbfb8aa3b, v1
	v_exp_f32_e32 v6, v6
	v_exp_f32_e32 v1, v1
	v_max_f32_e32 v4, v4, v4
	v_max_f32_e32 v4, 0, v4
	v_add_f32_e32 v6, 1.0, v6
	v_rcp_f32_e32 v6, v6
	v_add_f32_e32 v1, 1.0, v1
	v_rcp_f32_e32 v13, v1
	v_sqrt_f32_e32 v12, v4
	v_mul_f32_e32 v1, v6, v72
	v_lshl_add_u64 v[8:9], v[8:9], 0, v[52:53]
	v_add_f32_e32 v4, v1, v1
	v_lshl_add_u64 v[8:9], v[8:9], 2, s[42:43]
	v_cmp_ngt_f32_e32 vcc, s9, v4
	s_waitcnt lgkmcnt(0)
	v_lshlrev_b32_e32 v5, 16, v5
	v_mul_f32_e32 v5, v13, v5
	v_mul_f32_e32 v5, v12, v5
	v_cvt_pk_bf16_f32 v0, v0, v5
	global_store_dword v[8:9], v0, off
	s_and_saveexec_b64 s[2:3], vcc
	s_xor_b64 s[2:3], exec, s[2:3]
	v_fmamk_f32 v0, v4, 0x3ab60b61, v169
	v_fmaak_f32 v0, v4, v0, 0x3d2aaaab
	v_fmaak_f32 v0, v4, v0, 0x3e2aaaab
	v_fma_f32 v0, v4, v0, 0.5
	v_fma_f32 v0, v4, v0, 1.0
	v_mul_f32_e64 v0, v0, -v4
	s_andn2_saveexec_b64 s[2:3], s[2:3]
	v_mul_f32_e32 v0, 0x3fb8aa3b, v4
	v_exp_f32_e32 v0, v0
	s_nop 0
	v_sub_f32_e32 v0, 1.0, v0
	s_or_b64 exec, exec, s[2:3]
	ds_read_u16 v6, v120 offset:7232
	v_add_f32_e32 v7, v7, v74
	v_add_f32_e32 v2, v2, v67
	v_mul_f32_e32 v7, 0xbfb8aa3b, v7
	v_mul_f32_e32 v2, 0xbfb8aa3b, v2
	v_exp_f32_e32 v7, v7
	v_exp_f32_e32 v2, v2
	v_max_f32_e32 v0, v0, v0
	v_max_f32_e32 v0, 0, v0
	v_add_f32_e32 v7, 1.0, v7
	v_rcp_f32_e32 v7, v7
	v_sqrt_f32_e32 v8, v0
	v_add_f32_e32 v0, 1.0, v2
	v_rcp_f32_e32 v9, v0
	v_mul_f32_e32 v0, v7, v72
	v_lshl_add_u64 v[4:5], v[20:21], 0, v[52:53]
	v_add_f32_e32 v2, v0, v0
	v_lshl_add_u64 v[4:5], v[4:5], 2, s[42:43]
	v_cmp_ngt_f32_e32 vcc, s9, v2
	s_waitcnt lgkmcnt(0)
	v_lshlrev_b32_e32 v6, 16, v6
	v_mul_f32_e32 v6, v9, v6
	v_mul_f32_e32 v6, v8, v6
	v_cvt_pk_bf16_f32 v1, v1, v6
	global_store_dword v[4:5], v1, off
	s_and_saveexec_b64 s[2:3], vcc
	s_xor_b64 s[2:3], exec, s[2:3]
	v_fmamk_f32 v1, v2, 0x3ab60b61, v169
	v_fmaak_f32 v1, v2, v1, 0x3d2aaaab
	v_fmaak_f32 v1, v2, v1, 0x3e2aaaab
	v_fma_f32 v1, v2, v1, 0.5
	v_fma_f32 v1, v2, v1, 1.0
	v_mul_f32_e64 v1, v1, -v2
	s_andn2_saveexec_b64 s[2:3], s[2:3]
	v_mul_f32_e32 v1, 0x3fb8aa3b, v2
	v_exp_f32_e32 v1, v1
	s_nop 0
	v_sub_f32_e32 v1, 1.0, v1
	s_or_b64 exec, exec, s[2:3]
	ds_read_u16 v4, v120 offset:7376
	v_add_f32_e32 v2, v3, v67
	v_mul_f32_e32 v2, 0xbfb8aa3b, v2
	v_exp_f32_e32 v5, v2
	v_max_f32_e32 v1, v1, v1
	v_max_f32_e32 v1, 0, v1
	v_sqrt_f32_e32 v1, v1
	v_add_f32_e32 v5, 1.0, v5
	v_rcp_f32_e32 v5, v5
	v_lshl_add_u64 v[2:3], v[10:11], 0, v[52:53]
	v_lshl_add_u64 v[2:3], v[2:3], 2, s[42:43]
	s_waitcnt lgkmcnt(0)
	v_lshlrev_b32_e32 v4, 16, v4
	v_mul_f32_e32 v4, v5, v4
	v_mul_f32_e32 v1, v1, v4
	v_cvt_pk_bf16_f32 v0, v0, v1
	global_store_dword v[2:3], v0, off
	s_barrier
	s_mov_b32 s9, 0
